# scan_dir<1> prefetch block: decay constant for the next scan_dir<0> call no longer waited for in the block (scaled at that call's top)
# speedup vs baseline: 1.0024x; 1.0024x over previous
; __device__ __forceinline__ float bf2f(bf16_t b) { return __uint_as_float(((unsigned)b) << 16); }
; __device__ __forceinline__ float fast_sigmoid(float x) { return __builtin_amdgcn_rcpf(1.0f + __builtin_amdgcn_exp2f(-1.4426950408889634f * x)); }
; template <int DIR>
; __device__ __forceinline__ void scan_dir(PP p, const bf16_t* xs, const ScanW& w, ScanW& wn, int ndir, int nct, bool do_next, int n, int ct, int l31, int hl, int id, int rowbase, bool latent, float (&hf)[2][16]) {
;     ...
;     const float ba = w.ba, bi = w.bi, sp8l2 = w.sp8l2;
;     const bf16x8 (&wfa)[4] = w.wfa; const bf16x8 (&wfi)[4] = w.wfi;
;     float a[2][16], u[2][16];
; #pragma unroll
;     for (int rt = 0; rt < 2; ++rt) {
;         bf16x8 af[4];
; #pragma unroll
;         for (int st = 0; st < 4; ++st) af[st] = *(const bf16x8*)(xs + (32 * rt + l31) * XS + 64 * n + 16 * st + 8 * hl);
;         f32x16 ga, gi;
; #pragma unroll
;         for (int i = 0; i < 16; ++i) { ga[i] = 0.f; gi[i] = 0.f; }
; #pragma unroll
;         for (int st = 0; st < 4; ++st) { ga = __builtin_amdgcn_mfma_f32_32x32x16_bf16(af[st], wfa[st], ga, 0, 0, 0); gi = __builtin_amdgcn_mfma_f32_32x32x16_bf16(af[st], wfi[st], gi, 0, 0, 0); }
; #pragma unroll
;         for (int i = 0; i < 16; ++i) {
;             const int token = 32 * rt + 8 * (i >> 2) + 4 * hl + (i & 3);
;             const float xv = bf2f(xs[token * XS + ch]);
;             const float rr = fast_sigmoid(ga[i] + ba), ii = fast_sigmoid(gi[i] + bi);
;             const float la2 = rr * sp8l2;
;             const float av = __builtin_amdgcn_exp2f(la2);
;             const float t2 = la2 * 1.3862943611f;
;             float em1p = t2 * (1.0f + t2 * (0.5f + t2 * (0.16666667f + t2 * (0.041666668f + t2 * 0.0083333333f)))), em1e = __builtin_fmaf(av, av, -1.0f);
;             asm volatile("" : "+v"(em1p), "+v"(em1e));
;             const float em1 = (t2 > -0.1f) ? em1p : em1e;
;             a[rt][i] = av; u[rt][i] = __builtin_amdgcn_sqrtf(-em1) * (ii * xv);
;         }
.LBB0_378:
	ds_read_b128 v[2:5], v187
	s_lshl_b32 s48, s80, 5
	v_or_b32_e32 v66, s48, v150
	v_lshl_add_u32 v42, v66, 1, 0
	v_add_u32_e32 v0, v42, v151
	ds_read_u16 v43, v0
	ds_read_b128 v[34:37], v187 offset:32
	ds_read_b128 v[38:41], v187 offset:64
	s_waitcnt vmcnt(7) lgkmcnt(3)
	s_cmp_eq_u32 s80, 1
	s_cbranch_scc0 .Lscan_nomul1
	s_cmp_lg_u64 s[22:23], 0
	s_cbranch_scc0 .Lscan_nomul1
	v_mul_f32_e32 v194, 0x3fb8aa3b, v255
.Lscan_nomul1:
	v_mfma_f32_32x32x16_bf16 v[18:33], v[2:5], v[114:117], 0
	s_waitcnt vmcnt(2)
	v_mfma_f32_32x32x16_bf16 v[2:17], v[2:5], v[134:137], 0
	s_waitcnt lgkmcnt(1)
	v_mfma_f32_32x32x16_bf16 v[18:33], v[34:37], v[118:121], v[18:33]
	v_mfma_f32_32x32x16_bf16 v[2:17], v[34:37], v[126:129], v[2:17]
	ds_read_b128 v[34:37], v187 offset:96
	s_waitcnt lgkmcnt(1)
	v_mfma_f32_32x32x16_bf16 v[18:33], v[38:41], v[122:125], v[18:33]
	s_waitcnt vmcnt(1) lgkmcnt(0)
	ds_read_u16 v82, v0 offset:1040
	ds_read_u16 v83, v0 offset:2080
	ds_read_u16 v84, v0 offset:3120
	v_add_u32_e32 v113, v42, v152
	ds_read_u16 v85, v113
	ds_read_u16 v86, v0 offset:9360
	ds_read_u16 v87, v0 offset:10400
	ds_read_u16 v88, v0 offset:11440
	ds_read_u16 v89, v113 offset:8320
	ds_read_u16 v90, v0 offset:17680
	ds_read_u16 v91, v0 offset:18720
	ds_read_u16 v92, v0 offset:19760
	ds_read_u16 v93, v0 offset:34320
	ds_read_u16 v94, v0 offset:35360
	ds_read_u16 v95, v0 offset:36400
	ds_read_u16 v96, v0 offset:41600
	ds_read_u16 v97, v0 offset:42640
	ds_read_u16 v98, v0 offset:43680
	ds_read_u16 v99, v0 offset:44720
	ds_read_u16 v100, v0 offset:49920
	ds_read_u16 v101, v0 offset:50960
	ds_read_u16 v102, v0 offset:52000
	ds_read_u16 v103, v0 offset:53040
	ds_read_u16 v104, v0 offset:58240
	ds_read_u16 v105, v0 offset:59280
	ds_read_u16 v106, v0 offset:60320
	v_mfma_f32_32x32x16_bf16 v[18:33], v[34:37], v[138:141], v[18:33]
	v_mfma_f32_32x32x16_bf16 v[2:17], v[38:41], v[130:133], v[2:17]
	s_nop 10
	v_add_f32_e32 v18, v192, v18
	v_mul_f32_e32 v18, 0xbfb8aa3b, v18
	v_exp_f32_e32 v18, v18
	v_add_f32_e32 v19, v192, v19
	v_mul_f32_e32 v19, 0xbfb8aa3b, v19
	v_exp_f32_e32 v19, v19
	v_add_f32_e32 v18, 1.0, v18
	s_waitcnt vmcnt(0)
	v_mfma_f32_32x32x16_bf16 v[2:17], v[34:37], v[142:145], v[2:17]
	v_rcp_f32_e32 v18, v18
	v_add_f32_e32 v19, 1.0, v19
	v_rcp_f32_e32 v19, v19
	v_lshlrev_b32_e32 v34, 16, v43
	v_mul_f32_e32 v18, v194, v18
	v_exp_f32_e32 v50, v18
	v_mul_f32_e32 v18, 0x3fb17218, v18
	s_nop 4
	v_add_f32_e32 v2, v191, v2
	v_mul_f32_e32 v2, 0xbfb8aa3b, v2
	v_exp_f32_e32 v2, v2
	v_fmamk_f32 v35, v18, 0x3c088888, v186
	v_fmaak_f32 v35, v18, v35, 0x3e2aaaab
	v_fma_f32 v35, v18, v35, 0.5
	v_add_f32_e32 v2, 1.0, v2
	v_add_f32_e32 v3, v191, v3
	v_rcp_f32_e32 v2, v2
	v_fma_f32 v35, v18, v35, 1.0
	v_mul_f32_e32 v3, 0xbfb8aa3b, v3
	v_mul_f32_e32 v35, v18, v35
	v_fma_f32 v36, v50, v50, -1.0
	v_exp_f32_e32 v3, v3
	v_mul_f32_e32 v19, v194, v19
	v_cmp_lt_f32_e32 vcc, s76, v18
	v_exp_f32_e32 v52, v19
	v_mul_f32_e32 v19, 0x3fb17218, v19
	v_cndmask_b32_e32 v18, v36, v35, vcc
	v_fmamk_f32 v35, v19, 0x3c088888, v186
	v_mul_f32_e32 v2, v2, v34
	v_fmaak_f32 v35, v19, v35, 0x3e2aaaab
	v_sqrt_f32_e64 v18, -v18
	v_add_f32_e32 v3, 1.0, v3
	v_fma_f32 v35, v19, v35, 0.5
	v_add_f32_e32 v4, v191, v4
	v_rcp_f32_e32 v3, v3
	v_fma_f32 v35, v19, v35, 1.0
	v_mul_f32_e32 v4, 0xbfb8aa3b, v4
	v_mul_f32_e32 v35, v19, v35
	v_fma_f32 v36, v52, v52, -1.0
	v_cmp_lt_f32_e32 vcc, s76, v19
	v_exp_f32_e32 v4, v4
	v_mul_f32_e32 v2, v2, v18
	v_cndmask_b32_e32 v19, v36, v35, vcc
	v_sqrt_f32_e64 v19, -v19
	s_waitcnt lgkmcnt(0)
	v_lshlrev_b32_e32 v18, 16, v82
	v_mul_f32_e32 v3, v3, v18
	v_add_f32_e32 v4, 1.0, v4
	v_rcp_f32_e32 v4, v4
	v_mul_f32_e32 v3, v3, v19
	v_add_f32_e32 v19, v192, v20
	v_mul_f32_e32 v19, 0xbfb8aa3b, v19
	v_exp_f32_e32 v19, v19
	s_waitcnt lgkmcnt(0)
	v_lshlrev_b32_e32 v18, 16, v83
	v_mul_f32_e32 v4, v4, v18
	v_add_f32_e32 v18, v192, v21
	v_mul_f32_e32 v18, 0xbfb8aa3b, v18
	v_exp_f32_e32 v18, v18
	v_add_f32_e32 v19, 1.0, v19
	v_rcp_f32_e32 v19, v19
	v_add_f32_e32 v5, v191, v5
	v_add_f32_e32 v18, 1.0, v18
	v_rcp_f32_e32 v18, v18
	v_mul_f32_e32 v19, v194, v19
	v_exp_f32_e32 v51, v19
	v_mul_f32_e32 v19, 0x3fb17218, v19
	v_fmamk_f32 v20, v19, 0x3c088888, v186
	v_fmaak_f32 v20, v19, v20, 0x3e2aaaab
	v_mul_f32_e32 v18, v194, v18
	v_fma_f32 v20, v19, v20, 0.5
	v_mul_f32_e32 v5, 0xbfb8aa3b, v5
	v_exp_f32_e32 v54, v18
	v_mul_f32_e32 v18, 0x3fb17218, v18
	v_fma_f32 v20, v19, v20, 1.0
	v_exp_f32_e32 v5, v5
	v_fmamk_f32 v21, v18, 0x3c088888, v186
	v_mul_f32_e32 v20, v19, v20
	v_fma_f32 v34, v51, v51, -1.0
	v_fmaak_f32 v21, v18, v21, 0x3e2aaaab
	v_cmp_lt_f32_e32 vcc, s76, v19
	v_fma_f32 v21, v18, v21, 0.5
	v_fma_f32 v21, v18, v21, 1.0
	v_cndmask_b32_e32 v19, v34, v20, vcc
	v_sqrt_f32_e64 v19, -v19
	v_add_f32_e32 v5, 1.0, v5
	v_mul_f32_e32 v21, v18, v21
	v_fma_f32 v34, v54, v54, -1.0
	v_cmp_lt_f32_e32 vcc, s76, v18
	v_rcp_f32_e32 v5, v5
	v_add_f32_e32 v6, v191, v6
	v_cndmask_b32_e32 v18, v34, v21, vcc
	v_sqrt_f32_e64 v18, -v18
	v_mul_f32_e32 v6, 0xbfb8aa3b, v6
	v_mul_f32_e32 v4, v4, v19
	s_waitcnt lgkmcnt(0)
	v_lshlrev_b32_e32 v19, 16, v84
	v_exp_f32_e32 v6, v6
	v_mul_f32_e32 v5, v5, v19
	v_mul_f32_e32 v5, v18, v5
	v_add_u32_e32 v18, v42, v152
	v_add_f32_e32 v20, v192, v22
	v_mul_f32_e32 v20, 0xbfb8aa3b, v20
	v_add_f32_e32 v6, 1.0, v6
	v_exp_f32_e32 v20, v20
	v_rcp_f32_e32 v6, v6
	s_waitcnt lgkmcnt(0)
; __device__ __forceinline__ float bf2f(bf16_t b) { return __uint_as_float(((unsigned)b) << 16); }
; __device__ __forceinline__ float fast_sigmoid(float x) { return __builtin_amdgcn_rcpf(1.0f + __builtin_amdgcn_exp2f(-1.4426950408889634f * x)); }
; template <int DIR>
; __device__ __forceinline__ void scan_dir(PP p, const bf16_t* xs, const ScanW& w, ScanW& wn, int ndir, int nct, bool do_next, int n, int ct, int l31, int hl, int id, int rowbase, bool latent, float (&hf)[2][16]) {
;     ...
; #pragma unroll
;         for (int i = 0; i < 16; ++i) {
;             const int token = 32 * rt + 8 * (i >> 2) + 4 * hl + (i & 3);
;             const float xv = bf2f(xs[token * XS + ch]);
;             const float rr = fast_sigmoid(ga[i] + ba), ii = fast_sigmoid(gi[i] + bi);
;             const float la2 = rr * sp8l2;
;             const float av = __builtin_amdgcn_exp2f(la2);
;             const float t2 = la2 * 1.3862943611f;
;             float em1p = t2 * (1.0f + t2 * (0.5f + t2 * (0.16666667f + t2 * (0.041666668f + t2 * 0.0083333333f)))), em1e = __builtin_fmaf(av, av, -1.0f);
;             asm volatile("" : "+v"(em1p), "+v"(em1e));
;             const float em1 = (t2 > -0.1f) ? em1p : em1e;
;             a[rt][i] = av; u[rt][i] = __builtin_amdgcn_sqrtf(-em1) * (ii * xv);
;         }
	v_lshlrev_b32_e32 v19, 16, v85
	v_add_f32_e32 v7, v191, v7
	v_add_f32_e32 v20, 1.0, v20
	v_mul_f32_e32 v6, v6, v19
	v_add_f32_e32 v19, v192, v23
	v_rcp_f32_e32 v20, v20
	v_mul_f32_e32 v19, 0xbfb8aa3b, v19
	v_exp_f32_e32 v19, v19
	v_mul_f32_e32 v7, 0xbfb8aa3b, v7
	v_mul_f32_e32 v20, v194, v20
	v_exp_f32_e32 v53, v20
	v_mul_f32_e32 v20, 0x3fb17218, v20
	v_add_f32_e32 v19, 1.0, v19
	v_fmamk_f32 v21, v20, 0x3c088888, v186
	v_rcp_f32_e32 v19, v19
	v_fmaak_f32 v21, v20, v21, 0x3e2aaaab
	v_fma_f32 v21, v20, v21, 0.5
	v_fma_f32 v21, v20, v21, 1.0
	v_mul_f32_e32 v21, v20, v21
	v_fma_f32 v22, v53, v53, -1.0
	v_mul_f32_e32 v19, v194, v19
	v_cmp_lt_f32_e32 vcc, s76, v20
	v_exp_f32_e32 v55, v19
	v_mul_f32_e32 v19, 0x3fb17218, v19
	v_cndmask_b32_e32 v20, v22, v21, vcc
	v_exp_f32_e32 v7, v7
	v_fmamk_f32 v22, v19, 0x3c088888, v186
	v_fmaak_f32 v22, v19, v22, 0x3e2aaaab
	v_fma_f32 v22, v19, v22, 0.5
	v_fma_f32 v22, v19, v22, 1.0
	v_sqrt_f32_e64 v20, -v20
	v_add_f32_e32 v7, 1.0, v7
	v_mul_f32_e32 v22, v19, v22
	v_fma_f32 v23, v55, v55, -1.0
	v_cmp_lt_f32_e32 vcc, s76, v19
	v_rcp_f32_e32 v7, v7
	v_add_f32_e32 v8, v191, v8
	v_cndmask_b32_e32 v19, v23, v22, vcc
	v_sqrt_f32_e64 v19, -v19
	v_mul_f32_e32 v8, 0xbfb8aa3b, v8
	v_exp_f32_e32 v8, v8
	v_mul_f32_e32 v6, v20, v6
	s_waitcnt lgkmcnt(0)
	v_lshlrev_b32_e32 v20, 16, v86
	v_mul_f32_e32 v7, v7, v20
	v_mul_f32_e32 v7, v19, v7
	v_add_f32_e32 v20, v192, v24
	v_mul_f32_e32 v20, 0xbfb8aa3b, v20
	v_add_f32_e32 v8, 1.0, v8
	v_exp_f32_e32 v20, v20
	v_rcp_f32_e32 v8, v8
	s_waitcnt lgkmcnt(0)
	v_lshlrev_b32_e32 v19, 16, v87
	v_add_f32_e32 v9, v191, v9
	v_add_f32_e32 v20, 1.0, v20
	v_mul_f32_e32 v8, v8, v19
	v_add_f32_e32 v19, v192, v25
	v_rcp_f32_e32 v20, v20
	v_mul_f32_e32 v19, 0xbfb8aa3b, v19
	v_exp_f32_e32 v19, v19
	v_mul_f32_e32 v9, 0xbfb8aa3b, v9
	v_mul_f32_e32 v20, v194, v20
	v_exp_f32_e32 v67, v20
	v_mul_f32_e32 v20, 0x3fb17218, v20
	v_add_f32_e32 v19, 1.0, v19
	v_fmamk_f32 v21, v20, 0x3c088888, v186
	v_rcp_f32_e32 v19, v19
	v_fmaak_f32 v21, v20, v21, 0x3e2aaaab
	v_fma_f32 v21, v20, v21, 0.5
	v_fma_f32 v21, v20, v21, 1.0
	v_mul_f32_e32 v21, v20, v21
	v_fma_f32 v22, v67, v67, -1.0
	v_mul_f32_e32 v19, v194, v19
	v_cmp_lt_f32_e32 vcc, s76, v20
	v_exp_f32_e32 v69, v19
	v_mul_f32_e32 v19, 0x3fb17218, v19
	v_cndmask_b32_e32 v20, v22, v21, vcc
	v_exp_f32_e32 v9, v9
	v_fmamk_f32 v22, v19, 0x3c088888, v186
	v_fmaak_f32 v22, v19, v22, 0x3e2aaaab
	v_fma_f32 v22, v19, v22, 0.5
	v_fma_f32 v22, v19, v22, 1.0
	v_sqrt_f32_e64 v20, -v20
	v_add_f32_e32 v9, 1.0, v9
	v_mul_f32_e32 v22, v19, v22
	v_fma_f32 v23, v69, v69, -1.0
	v_cmp_lt_f32_e32 vcc, s76, v19
	v_rcp_f32_e32 v9, v9
	v_add_f32_e32 v10, v191, v10
	v_cndmask_b32_e32 v19, v23, v22, vcc
	v_sqrt_f32_e64 v19, -v19
	v_mul_f32_e32 v10, 0xbfb8aa3b, v10
	v_exp_f32_e32 v10, v10
	v_mul_f32_e32 v8, v20, v8
	s_waitcnt lgkmcnt(0)
	v_lshlrev_b32_e32 v20, 16, v88
	v_mul_f32_e32 v9, v9, v20
	v_mul_f32_e32 v76, v19, v9
	v_add_f32_e32 v19, v192, v26
	v_mul_f32_e32 v19, 0xbfb8aa3b, v19
	v_add_f32_e32 v10, 1.0, v10
	v_exp_f32_e32 v19, v19
	v_rcp_f32_e32 v10, v10
	s_waitcnt lgkmcnt(0)
	v_lshlrev_b32_e32 v9, 16, v89
	v_add_f32_e32 v11, v191, v11
	v_add_f32_e32 v19, 1.0, v19
	v_mul_f32_e32 v9, v10, v9
	v_add_f32_e32 v10, v192, v27
	v_rcp_f32_e32 v19, v19
	v_mul_f32_e32 v10, 0xbfb8aa3b, v10
	v_exp_f32_e32 v10, v10
	v_mul_f32_e32 v11, 0xbfb8aa3b, v11
	v_mul_f32_e32 v19, v194, v19
	v_exp_f32_e32 v68, v19
	v_mul_f32_e32 v19, 0x3fb17218, v19
	v_add_f32_e32 v10, 1.0, v10
	v_fmamk_f32 v20, v19, 0x3c088888, v186
	v_rcp_f32_e32 v10, v10
	v_fmaak_f32 v20, v19, v20, 0x3e2aaaab
	v_fma_f32 v20, v19, v20, 0.5
	v_fma_f32 v20, v19, v20, 1.0
	v_mul_f32_e32 v20, v19, v20
	v_fma_f32 v21, v68, v68, -1.0
	v_mul_f32_e32 v10, v194, v10
	v_cmp_lt_f32_e32 vcc, s76, v19
	v_exp_f32_e32 v71, v10
	v_mul_f32_e32 v10, 0x3fb17218, v10
	v_cndmask_b32_e32 v19, v21, v20, vcc
	v_exp_f32_e32 v11, v11
	v_fmamk_f32 v21, v10, 0x3c088888, v186
	v_fmaak_f32 v21, v10, v21, 0x3e2aaaab
	v_fma_f32 v21, v10, v21, 0.5
	v_fma_f32 v21, v10, v21, 1.0
	v_sqrt_f32_e64 v19, -v19
	v_add_f32_e32 v11, 1.0, v11
	v_mul_f32_e32 v21, v10, v21
	v_fma_f32 v22, v71, v71, -1.0
	v_cmp_lt_f32_e32 vcc, s76, v10
	v_rcp_f32_e32 v11, v11
	v_mul_f32_e32 v74, v19, v9
	v_cndmask_b32_e32 v10, v22, v21, vcc
	v_sqrt_f32_e64 v10, -v10
	s_waitcnt lgkmcnt(0)
	v_lshlrev_b32_e32 v9, 16, v90
	v_mul_f32_e32 v9, v11, v9
	v_add_f32_e32 v11, v191, v12
	v_mul_f32_e32 v73, v10, v9
	v_add_f32_e32 v10, v192, v28
	v_mul_f32_e32 v10, 0xbfb8aa3b, v10
	v_exp_f32_e32 v10, v10
	v_mul_f32_e32 v11, 0xbfb8aa3b, v11
	v_exp_f32_e32 v11, v11
	v_add_f32_e32 v10, 1.0, v10
	v_rcp_f32_e32 v10, v10
	s_waitcnt lgkmcnt(0)
; __device__ __forceinline__ float bf2f(bf16_t b) { return __uint_as_float(((unsigned)b) << 16); }
; __device__ __forceinline__ float fast_sigmoid(float x) { return __builtin_amdgcn_rcpf(1.0f + __builtin_amdgcn_exp2f(-1.4426950408889634f * x)); }
; template <int DIR>
; __device__ __forceinline__ void scan_dir(PP p, const bf16_t* xs, const ScanW& w, ScanW& wn, int ndir, int nct, bool do_next, int n, int ct, int l31, int hl, int id, int rowbase, bool latent, float (&hf)[2][16]) {
;     ...
;         bf16x8 af[4];
; #pragma unroll
;         for (int st = 0; st < 4; ++st) af[st] = *(const bf16x8*)(xs + (32 * rt + l31) * XS + 64 * n + 16 * st + 8 * hl);
;         f32x16 ga, gi;
; #pragma unroll
;         for (int i = 0; i < 16; ++i) { ga[i] = 0.f; gi[i] = 0.f; }
; #pragma unroll
;         for (int st = 0; st < 4; ++st) { ga = __builtin_amdgcn_mfma_f32_32x32x16_bf16(af[st], wfa[st], ga, 0, 0, 0); gi = __builtin_amdgcn_mfma_f32_32x32x16_bf16(af[st], wfi[st], gi, 0, 0, 0); }
; #pragma unroll
;         for (int i = 0; i < 16; ++i) {
;             const int token = 32 * rt + 8 * (i >> 2) + 4 * hl + (i & 3);
;             const float xv = bf2f(xs[token * XS + ch]);
;             const float rr = fast_sigmoid(ga[i] + ba), ii = fast_sigmoid(gi[i] + bi);
;             const float la2 = rr * sp8l2;
;             const float av = __builtin_amdgcn_exp2f(la2);
;             const float t2 = la2 * 1.3862943611f;
;             float em1p = t2 * (1.0f + t2 * (0.5f + t2 * (0.16666667f + t2 * (0.041666668f + t2 * 0.0083333333f)))), em1e = __builtin_fmaf(av, av, -1.0f);
;             asm volatile("" : "+v"(em1p), "+v"(em1e));
;             const float em1 = (t2 > -0.1f) ? em1p : em1e;
;             a[rt][i] = av; u[rt][i] = __builtin_amdgcn_sqrtf(-em1) * (ii * xv);
;         }
	v_lshlrev_b32_e32 v9, 16, v91
	v_add_f32_e32 v11, 1.0, v11
	v_rcp_f32_e32 v11, v11
	v_mul_f32_e32 v10, v194, v10
	v_exp_f32_e32 v70, v10
	v_mul_f32_e32 v10, 0x3fb17218, v10
	v_fmamk_f32 v12, v10, 0x3c088888, v186
	v_fmaak_f32 v12, v10, v12, 0x3e2aaaab
	v_fma_f32 v12, v10, v12, 0.5
	v_fma_f32 v12, v10, v12, 1.0
	v_mul_f32_e32 v12, v10, v12
	v_fma_f32 v19, v70, v70, -1.0
	v_cmp_lt_f32_e32 vcc, s76, v10
	v_mul_f32_e32 v9, v11, v9
	v_add_f32_e32 v11, v191, v13
	v_cndmask_b32_e32 v10, v19, v12, vcc
	v_add_f32_e32 v12, v192, v29
	v_mul_f32_e32 v12, 0xbfb8aa3b, v12
	v_exp_f32_e32 v12, v12
	v_sqrt_f32_e64 v19, -v10
	v_mul_f32_e32 v11, 0xbfb8aa3b, v11
	v_exp_f32_e32 v21, v11
	v_add_f32_e32 v10, 1.0, v12
	v_rcp_f32_e32 v10, v10
	v_add_f32_e32 v11, v192, v30
	v_mul_f32_e32 v11, 0xbfb8aa3b, v11
	v_exp_f32_e32 v11, v11
	v_mul_f32_e32 v10, v194, v10
	v_mul_f32_e32 v22, 0x3fb17218, v10
	v_exp_f32_e32 v75, v10
	v_fmamk_f32 v10, v22, 0x3c088888, v186
	v_fmaak_f32 v10, v22, v10, 0x3e2aaaab
	v_fma_f32 v10, v22, v10, 0.5
	v_fma_f32 v10, v22, v10, 1.0
	v_mul_f32_e32 v23, v22, v10
	v_add_f32_e32 v10, 1.0, v11
	v_rcp_f32_e32 v10, v10
	v_add_f32_e32 v11, v192, v31
	v_mul_f32_e32 v11, 0xbfb8aa3b, v11
	v_exp_f32_e32 v11, v11
	v_mul_f32_e32 v10, v194, v10
	v_mul_f32_e32 v60, 0x3fb17218, v10
	v_exp_f32_e32 v72, v10
	v_fmamk_f32 v10, v60, 0x3c088888, v186
	v_fmaak_f32 v10, v60, v10, 0x3e2aaaab
	v_fma_f32 v10, v60, v10, 0.5
	v_fma_f32 v10, v60, v10, 1.0
	v_mul_f32_e32 v61, v60, v10
	v_add_f32_e32 v10, 1.0, v11
	v_rcp_f32_e32 v10, v10
	v_add_f32_e32 v11, v192, v32
	v_mul_f32_e32 v11, 0xbfb8aa3b, v11
	v_exp_f32_e32 v11, v11
	v_mul_f32_e32 v10, v194, v10
	v_mul_f32_e32 v64, 0x3fb17218, v10
	v_exp_f32_e32 v78, v10
	v_fmamk_f32 v10, v64, 0x3c088888, v186
	v_fmaak_f32 v10, v64, v10, 0x3e2aaaab
	v_fma_f32 v10, v64, v10, 0.5
	v_fma_f32 v10, v64, v10, 1.0
	v_mul_f32_e32 v65, v64, v10
	v_add_f32_e32 v10, 1.0, v11
	v_rcp_f32_e32 v10, v10
	v_add_f32_e32 v11, v192, v33
	v_mul_f32_e32 v11, 0xbfb8aa3b, v11
	v_exp_f32_e32 v11, v11
	v_mul_f32_e32 v10, v194, v10
	v_mul_f32_e32 v146, 0x3fb17218, v10
	v_exp_f32_e32 v77, v10
	v_fmamk_f32 v10, v146, 0x3c088888, v186
	v_fmaak_f32 v10, v146, v10, 0x3e2aaaab
	v_fma_f32 v10, v146, v10, 0.5
	v_fma_f32 v10, v146, v10, 1.0
	v_mul_f32_e32 v147, v146, v10
	v_add_f32_e32 v10, 1.0, v11
	v_rcp_f32_e32 v10, v10
	v_fma_f32 v24, v75, v75, -1.0
	v_mul_f32_e32 v209, v19, v9
	v_mul_f32_e32 v10, v194, v10
	v_mul_f32_e32 v156, 0x3fb17218, v10
	v_add_f32_e32 v19, 1.0, v21
	v_cmp_lt_f32_e32 vcc, s76, v22
	v_exp_f32_e32 v79, v10
	v_fmamk_f32 v10, v156, 0x3c088888, v186
	v_rcp_f32_e32 v35, v19
	v_cndmask_b32_e32 v19, v24, v23, vcc
	v_fmaak_f32 v10, v156, v10, 0x3e2aaaab
	v_sqrt_f32_e64 v36, -v19
	v_fma_f32 v10, v156, v10, 0.5
	v_fma_f32 v10, v156, v10, 1.0
	s_waitcnt lgkmcnt(0)
	v_lshlrev_b32_e32 v9, 16, v92
	v_fma_f32 v62, v72, v72, -1.0
	v_fma_f32 v80, v78, v78, -1.0
	v_fma_f32 v154, v77, v77, -1.0
	v_mul_f32_e32 v158, v156, v10
	v_fma_f32 v159, v79, v79, -1.0
	v_mul_f32_e32 v9, v35, v9
	ds_read_u16 v34, v18 offset:16640
	ds_read_u16 v63, v0 offset:26000
	ds_read_u16 v81, v0 offset:27040
	ds_read_u16 v155, v0 offset:28080
	ds_read_b128 v[10:13], v187 offset:33280
	ds_read_u16 v195, v18 offset:24960
	v_mul_f32_e32 v217, v36, v9
	v_add_f32_e32 v9, v191, v14
	v_mul_f32_e32 v9, 0xbfb8aa3b, v9
	v_exp_f32_e32 v9, v9
	v_add_f32_e32 v15, v191, v15
	v_mul_f32_e32 v15, 0xbfb8aa3b, v15
	v_exp_f32_e32 v15, v15
	v_add_f32_e32 v9, 1.0, v9
	v_rcp_f32_e32 v9, v9
	ds_read_b128 v[56:59], v187 offset:33312
	s_waitcnt lgkmcnt(6)
	v_lshlrev_b32_e32 v14, 16, v34
	s_waitcnt lgkmcnt(2)
	v_mfma_f32_32x32x16_bf16 v[34:49], v[10:13], v[134:137], 0
	v_cmp_lt_f32_e32 vcc, s76, v60
	v_mul_f32_e32 v9, v9, v14
	v_add_f32_e32 v14, 1.0, v15
	v_rcp_f32_e32 v14, v14
	v_mfma_f32_32x32x16_bf16 v[18:33], v[10:13], v[114:117], 0
	v_cndmask_b32_e32 v10, v62, v61, vcc
	v_sqrt_f32_e64 v60, -v10
	ds_read_b128 v[10:13], v187 offset:33344
	v_cmp_lt_f32_e32 vcc, s76, v64
	v_mul_f32_e32 v197, v60, v9
	v_lshlrev_b32_e32 v9, 16, v63
	v_mul_f32_e32 v9, v14, v9
	v_add_f32_e32 v14, v191, v16
	s_waitcnt lgkmcnt(1)
	v_mfma_f32_32x32x16_bf16 v[34:49], v[56:59], v[126:129], v[34:49]
	v_mul_f32_e32 v14, 0xbfb8aa3b, v14
	v_exp_f32_e32 v14, v14
	v_cndmask_b32_e32 v15, v80, v65, vcc
	v_sqrt_f32_e64 v15, -v15
	v_cmp_lt_f32_e32 vcc, s76, v146
	v_add_f32_e32 v14, 1.0, v14
	v_mul_f32_e32 v199, v15, v9
	v_mfma_f32_32x32x16_bf16 v[18:33], v[56:59], v[118:121], v[18:33]
	v_rcp_f32_e32 v56, v14
	v_add_f32_e32 v14, v191, v17
	v_mul_f32_e32 v57, 0xbfb8aa3b, v14
	ds_read_b128 v[14:17], v187 offset:33376
	v_lshlrev_b32_e32 v9, 16, v81
	v_mul_f32_e32 v9, v56, v9
	s_waitcnt lgkmcnt(1)
	v_mfma_f32_32x32x16_bf16 v[34:49], v[10:13], v[130:133], v[34:49]
	v_mfma_f32_32x32x16_bf16 v[18:33], v[10:13], v[122:125], v[18:33]
	v_exp_f32_e32 v10, v57
	v_cndmask_b32_e32 v11, v154, v147, vcc
	v_sqrt_f32_e64 v11, -v11
	v_cmp_lt_f32_e32 vcc, s76, v156
	v_add_f32_e32 v10, 1.0, v10
	v_rcp_f32_e32 v10, v10
	v_cndmask_b32_e32 v12, v159, v158, vcc
	s_waitcnt lgkmcnt(0)
; __device__ __forceinline__ float bf2f(bf16_t b) { return __uint_as_float(((unsigned)b) << 16); }
; __device__ __forceinline__ float fast_sigmoid(float x) { return __builtin_amdgcn_rcpf(1.0f + __builtin_amdgcn_exp2f(-1.4426950408889634f * x)); }
; template <int DIR>
; __device__ __forceinline__ void scan_dir(PP p, const bf16_t* xs, const ScanW& w, ScanW& wn, int ndir, int nct, bool do_next, int n, int ct, int l31, int hl, int id, int rowbase, bool latent, float (&hf)[2][16]) {
;     ...
; #pragma unroll
;         for (int i = 0; i < 16; ++i) {
;             const int token = 32 * rt + 8 * (i >> 2) + 4 * hl + (i & 3);
;             const float xv = bf2f(xs[token * XS + ch]);
;             const float rr = fast_sigmoid(ga[i] + ba), ii = fast_sigmoid(gi[i] + bi);
;             const float la2 = rr * sp8l2;
;             const float av = __builtin_amdgcn_exp2f(la2);
;             const float t2 = la2 * 1.3862943611f;
;             float em1p = t2 * (1.0f + t2 * (0.5f + t2 * (0.16666667f + t2 * (0.041666668f + t2 * 0.0083333333f)))), em1e = __builtin_fmaf(av, av, -1.0f);
;             asm volatile("" : "+v"(em1p), "+v"(em1e));
;             const float em1 = (t2 > -0.1f) ? em1p : em1e;
;             a[rt][i] = av; u[rt][i] = __builtin_amdgcn_sqrtf(-em1) * (ii * xv);
;         }
	v_mfma_f32_32x32x16_bf16 v[34:49], v[14:17], v[142:145], v[34:49]
	v_sqrt_f32_e64 v12, -v12
	v_mul_f32_e32 v204, v11, v9
	v_lshlrev_b32_e32 v9, 16, v155
	v_mul_f32_e32 v9, v10, v9
	v_mul_f32_e32 v202, v12, v9
	v_lshlrev_b32_e32 v11, 16, v195
	s_nop 5
	v_add_f32_e32 v10, v191, v34
	v_mfma_f32_32x32x16_bf16 v[18:33], v[14:17], v[138:141], v[18:33]
	v_mul_f32_e32 v10, 0xbfb8aa3b, v10
	v_exp_f32_e32 v10, v10
	s_nop 0
	v_add_f32_e32 v10, 1.0, v10
	v_rcp_f32_e32 v10, v10
	s_nop 6
	v_add_f32_e32 v9, v192, v18
	v_mul_f32_e32 v9, 0xbfb8aa3b, v9
	v_exp_f32_e32 v9, v9
	v_mul_f32_e32 v10, v10, v11
	v_add_f32_e32 v11, v192, v19
	v_mul_f32_e32 v11, 0xbfb8aa3b, v11
	v_add_f32_e32 v9, 1.0, v9
	v_rcp_f32_e32 v9, v9
	v_exp_f32_e32 v11, v11
	v_mul_f32_e32 v9, v194, v9
	v_exp_f32_e32 v80, v9
	v_mul_f32_e32 v9, 0x3fb17218, v9
	v_fmamk_f32 v12, v9, 0x3c088888, v186
	v_fmaak_f32 v12, v9, v12, 0x3e2aaaab
	v_add_f32_e32 v11, 1.0, v11
	v_fma_f32 v12, v9, v12, 0.5
	v_rcp_f32_e32 v11, v11
	v_fma_f32 v12, v9, v12, 1.0
	v_mul_f32_e32 v12, v9, v12
	v_fma_f32 v13, v80, v80, -1.0
	v_cmp_lt_f32_e32 vcc, s76, v9
	v_mul_f32_e32 v11, v194, v11
	v_exp_f32_e32 v146, v11
	v_cndmask_b32_e32 v9, v13, v12, vcc
	v_add_f32_e32 v12, v191, v35
	v_mul_f32_e32 v12, 0xbfb8aa3b, v12
	v_mul_f32_e32 v11, 0x3fb17218, v11
	v_exp_f32_e32 v12, v12
	v_fmamk_f32 v14, v11, 0x3c088888, v186
	v_fmaak_f32 v14, v11, v14, 0x3e2aaaab
	v_fma_f32 v14, v11, v14, 0.5
	v_fma_f32 v14, v11, v14, 1.0
	v_sqrt_f32_e64 v9, -v9
	v_add_f32_e32 v12, 1.0, v12
	v_mul_f32_e32 v14, v11, v14
	v_fma_f32 v15, v146, v146, -1.0
	v_cmp_lt_f32_e32 vcc, s76, v11
	v_rcp_f32_e32 v12, v12
	v_mul_f32_e32 v196, v10, v9
	v_cndmask_b32_e32 v11, v15, v14, vcc
	v_sqrt_f32_e64 v11, -v11
	s_waitcnt lgkmcnt(0)
	v_lshlrev_b32_e32 v9, 16, v93
	v_mul_f32_e32 v9, v12, v9
	v_add_f32_e32 v10, v192, v20
	v_mul_f32_e32 v195, v9, v11
	v_add_f32_e32 v11, v191, v36
	v_mul_f32_e32 v11, 0xbfb8aa3b, v11
	v_exp_f32_e32 v11, v11
	v_mul_f32_e32 v10, 0xbfb8aa3b, v10
	v_exp_f32_e32 v10, v10
	v_add_f32_e32 v11, 1.0, v11
	v_rcp_f32_e32 v11, v11
	v_add_f32_e32 v10, 1.0, v10
	v_rcp_f32_e32 v10, v10
	s_waitcnt lgkmcnt(0)
	v_lshlrev_b32_e32 v9, 16, v94
	v_mul_f32_e32 v9, v11, v9
	v_add_f32_e32 v11, v192, v21
	v_mul_f32_e32 v11, 0xbfb8aa3b, v11
	v_exp_f32_e32 v11, v11
	v_mul_f32_e32 v10, v194, v10
	v_exp_f32_e32 v81, v10
	v_mul_f32_e32 v10, 0x3fb17218, v10
	v_fmamk_f32 v12, v10, 0x3c088888, v186
	v_fmaak_f32 v12, v10, v12, 0x3e2aaaab
	v_add_f32_e32 v11, 1.0, v11
	v_fma_f32 v12, v10, v12, 0.5
	v_rcp_f32_e32 v11, v11
	v_fma_f32 v12, v10, v12, 1.0
	v_mul_f32_e32 v12, v10, v12
	v_fma_f32 v13, v81, v81, -1.0
	v_cmp_lt_f32_e32 vcc, s76, v10
	v_mul_f32_e32 v11, v194, v11
	v_exp_f32_e32 v198, v11
	v_cndmask_b32_e32 v10, v13, v12, vcc
	v_add_f32_e32 v12, v191, v37
	v_mul_f32_e32 v12, 0xbfb8aa3b, v12
	v_mul_f32_e32 v11, 0x3fb17218, v11
	v_exp_f32_e32 v12, v12
	v_fmamk_f32 v14, v11, 0x3c088888, v186
	v_fmaak_f32 v14, v11, v14, 0x3e2aaaab
	v_fma_f32 v14, v11, v14, 0.5
	v_fma_f32 v14, v11, v14, 1.0
	v_sqrt_f32_e64 v10, -v10
	v_add_f32_e32 v12, 1.0, v12
	v_mul_f32_e32 v14, v11, v14
	v_fma_f32 v15, v198, v198, -1.0
	v_cmp_lt_f32_e32 vcc, s76, v11
	v_rcp_f32_e32 v12, v12
	v_mul_f32_e32 v214, v9, v10
	v_cndmask_b32_e32 v11, v15, v14, vcc
	v_sqrt_f32_e64 v11, -v11
	s_waitcnt lgkmcnt(0)
	v_lshlrev_b32_e32 v9, 16, v95
	v_mul_f32_e32 v9, v12, v9
	v_add_f32_e32 v10, v192, v22
	v_mul_f32_e32 v211, v11, v9
	v_add_f32_e32 v11, v191, v38
	v_mul_f32_e32 v11, 0xbfb8aa3b, v11
	v_exp_f32_e32 v11, v11
	v_mul_f32_e32 v10, 0xbfb8aa3b, v10
	v_exp_f32_e32 v10, v10
	v_add_f32_e32 v11, 1.0, v11
	v_rcp_f32_e32 v11, v11
	v_add_f32_e32 v10, 1.0, v10
	v_rcp_f32_e32 v10, v10
	s_waitcnt lgkmcnt(0)
	v_lshlrev_b32_e32 v9, 16, v96
	v_mul_f32_e32 v9, v11, v9
	v_add_f32_e32 v11, v192, v23
	v_mul_f32_e32 v11, 0xbfb8aa3b, v11
	v_exp_f32_e32 v11, v11
	v_mul_f32_e32 v10, v194, v10
	v_exp_f32_e32 v147, v10
	v_mul_f32_e32 v10, 0x3fb17218, v10
	v_fmamk_f32 v12, v10, 0x3c088888, v186
	v_fmaak_f32 v12, v10, v12, 0x3e2aaaab
	v_add_f32_e32 v11, 1.0, v11
	v_fma_f32 v12, v10, v12, 0.5
	v_rcp_f32_e32 v11, v11
	v_fma_f32 v12, v10, v12, 1.0
	v_mul_f32_e32 v12, v10, v12
	v_fma_f32 v13, v147, v147, -1.0
	v_cmp_lt_f32_e32 vcc, s76, v10
	v_mul_f32_e32 v11, v194, v11
	v_exp_f32_e32 v201, v11
	v_cndmask_b32_e32 v10, v13, v12, vcc
	v_add_f32_e32 v12, v191, v39
	v_mul_f32_e32 v12, 0xbfb8aa3b, v12
	v_mul_f32_e32 v11, 0x3fb17218, v11
	v_exp_f32_e32 v12, v12
	v_fmamk_f32 v14, v11, 0x3c088888, v186
	v_fmaak_f32 v14, v11, v14, 0x3e2aaaab
	v_fma_f32 v14, v11, v14, 0.5
	v_fma_f32 v14, v11, v14, 1.0
	v_sqrt_f32_e64 v10, -v10
	v_add_f32_e32 v12, 1.0, v12
	v_mul_f32_e32 v14, v11, v14
	v_fma_f32 v15, v201, v201, -1.0
	v_cmp_lt_f32_e32 vcc, s76, v11
	v_rcp_f32_e32 v12, v12
	v_mul_f32_e32 v206, v10, v9
	v_cndmask_b32_e32 v11, v15, v14, vcc
	v_sqrt_f32_e64 v11, -v11
	s_waitcnt lgkmcnt(0)
	v_lshlrev_b32_e32 v9, 16, v97
	v_mul_f32_e32 v9, v12, v9
	v_add_f32_e32 v10, v192, v24
	v_mul_f32_e32 v205, v11, v9
	v_add_f32_e32 v11, v191, v40
	v_mul_f32_e32 v11, 0xbfb8aa3b, v11
	v_exp_f32_e32 v11, v11
	v_mul_f32_e32 v10, 0xbfb8aa3b, v10
	v_exp_f32_e32 v10, v10
	v_add_f32_e32 v11, 1.0, v11
	v_rcp_f32_e32 v11, v11
	v_add_f32_e32 v10, 1.0, v10
	v_rcp_f32_e32 v10, v10
	s_waitcnt lgkmcnt(0)
; __device__ __forceinline__ float bf2f(bf16_t b) { return __uint_as_float(((unsigned)b) << 16); }
; __device__ __forceinline__ float fast_sigmoid(float x) { return __builtin_amdgcn_rcpf(1.0f + __builtin_amdgcn_exp2f(-1.4426950408889634f * x)); }
; template <int DIR>
; __device__ __forceinline__ void scan_dir(PP p, const bf16_t* xs, const ScanW& w, ScanW& wn, int ndir, int nct, bool do_next, int n, int ct, int l31, int hl, int id, int rowbase, bool latent, float (&hf)[2][16]) {
;     ...
; #pragma unroll
;         for (int i = 0; i < 16; ++i) {
;             const int token = 32 * rt + 8 * (i >> 2) + 4 * hl + (i & 3);
;             const float xv = bf2f(xs[token * XS + ch]);
;             const float rr = fast_sigmoid(ga[i] + ba), ii = fast_sigmoid(gi[i] + bi);
;             const float la2 = rr * sp8l2;
;             const float av = __builtin_amdgcn_exp2f(la2);
;             const float t2 = la2 * 1.3862943611f;
;             float em1p = t2 * (1.0f + t2 * (0.5f + t2 * (0.16666667f + t2 * (0.041666668f + t2 * 0.0083333333f)))), em1e = __builtin_fmaf(av, av, -1.0f);
;             asm volatile("" : "+v"(em1p), "+v"(em1e));
;             const float em1 = (t2 > -0.1f) ? em1p : em1e;
;             a[rt][i] = av; u[rt][i] = __builtin_amdgcn_sqrtf(-em1) * (ii * xv);
;         }
	v_lshlrev_b32_e32 v9, 16, v98
	v_mul_f32_e32 v9, v11, v9
	v_add_f32_e32 v11, v192, v25
	v_mul_f32_e32 v11, 0xbfb8aa3b, v11
	v_exp_f32_e32 v11, v11
	v_mul_f32_e32 v10, v194, v10
	v_exp_f32_e32 v200, v10
	v_mul_f32_e32 v10, 0x3fb17218, v10
	v_fmamk_f32 v12, v10, 0x3c088888, v186
	v_fmaak_f32 v12, v10, v12, 0x3e2aaaab
	v_add_f32_e32 v11, 1.0, v11
	v_fma_f32 v12, v10, v12, 0.5
	v_rcp_f32_e32 v11, v11
	v_fma_f32 v12, v10, v12, 1.0
	v_mul_f32_e32 v12, v10, v12
	v_fma_f32 v13, v200, v200, -1.0
	v_cmp_lt_f32_e32 vcc, s76, v10
	v_mul_f32_e32 v11, v194, v11
	v_exp_f32_e32 v207, v11
	v_cndmask_b32_e32 v10, v13, v12, vcc
	v_add_f32_e32 v12, v191, v41
	v_mul_f32_e32 v12, 0xbfb8aa3b, v12
	v_mul_f32_e32 v11, 0x3fb17218, v11
	v_exp_f32_e32 v12, v12
	v_fmamk_f32 v14, v11, 0x3c088888, v186
	v_fmaak_f32 v14, v11, v14, 0x3e2aaaab
	v_fma_f32 v14, v11, v14, 0.5
	v_fma_f32 v14, v11, v14, 1.0
	v_sqrt_f32_e64 v10, -v10
	v_add_f32_e32 v12, 1.0, v12
	v_mul_f32_e32 v14, v11, v14
	v_fma_f32 v15, v207, v207, -1.0
	v_cmp_lt_f32_e32 vcc, s76, v11
	v_rcp_f32_e32 v12, v12
	v_mul_f32_e32 v222, v10, v9
	v_cndmask_b32_e32 v11, v15, v14, vcc
	v_sqrt_f32_e64 v11, -v11
	s_waitcnt lgkmcnt(0)
	v_lshlrev_b32_e32 v9, 16, v99
	v_mul_f32_e32 v9, v12, v9
	v_add_f32_e32 v10, v192, v26
	v_mul_f32_e32 v221, v11, v9
	v_add_f32_e32 v11, v191, v42
	v_mul_f32_e32 v11, 0xbfb8aa3b, v11
	v_exp_f32_e32 v11, v11
	v_mul_f32_e32 v10, 0xbfb8aa3b, v10
	v_exp_f32_e32 v10, v10
	v_add_f32_e32 v11, 1.0, v11
	v_rcp_f32_e32 v11, v11
	v_add_f32_e32 v10, 1.0, v10
	v_rcp_f32_e32 v10, v10
	s_waitcnt lgkmcnt(0)
	v_lshlrev_b32_e32 v9, 16, v100
	v_mul_f32_e32 v9, v11, v9
	v_add_f32_e32 v11, v192, v27
	v_mul_f32_e32 v11, 0xbfb8aa3b, v11
	v_exp_f32_e32 v11, v11
	v_mul_f32_e32 v10, v194, v10
	v_exp_f32_e32 v203, v10
	v_mul_f32_e32 v10, 0x3fb17218, v10
	v_fmamk_f32 v12, v10, 0x3c088888, v186
	v_fmaak_f32 v12, v10, v12, 0x3e2aaaab
	v_add_f32_e32 v11, 1.0, v11
	v_fma_f32 v12, v10, v12, 0.5
	v_rcp_f32_e32 v11, v11
	v_fma_f32 v12, v10, v12, 1.0
	v_mul_f32_e32 v12, v10, v12
	v_fma_f32 v13, v203, v203, -1.0
	v_cmp_lt_f32_e32 vcc, s76, v10
	v_mul_f32_e32 v11, v194, v11
	v_exp_f32_e32 v210, v11
	v_cndmask_b32_e32 v10, v13, v12, vcc
	v_add_f32_e32 v12, v191, v43
	v_mul_f32_e32 v12, 0xbfb8aa3b, v12
	v_mul_f32_e32 v11, 0x3fb17218, v11
	v_exp_f32_e32 v12, v12
	v_fmamk_f32 v14, v11, 0x3c088888, v186
	v_fmaak_f32 v14, v11, v14, 0x3e2aaaab
	v_fma_f32 v14, v11, v14, 0.5
	v_fma_f32 v14, v11, v14, 1.0
	v_sqrt_f32_e64 v10, -v10
	v_add_f32_e32 v12, 1.0, v12
	v_mul_f32_e32 v14, v11, v14
	v_fma_f32 v15, v210, v210, -1.0
	v_cmp_lt_f32_e32 vcc, s76, v11
	v_rcp_f32_e32 v12, v12
	v_mul_f32_e32 v216, v10, v9
	v_cndmask_b32_e32 v11, v15, v14, vcc
	v_sqrt_f32_e64 v11, -v11
	s_waitcnt lgkmcnt(0)
	v_lshlrev_b32_e32 v9, 16, v101
	v_mul_f32_e32 v9, v12, v9
	v_add_f32_e32 v10, v192, v28
	v_mul_f32_e32 v215, v11, v9
	v_add_f32_e32 v11, v191, v44
	v_mul_f32_e32 v11, 0xbfb8aa3b, v11
	v_exp_f32_e32 v11, v11
	v_mul_f32_e32 v10, 0xbfb8aa3b, v10
	v_exp_f32_e32 v10, v10
	v_add_f32_e32 v11, 1.0, v11
	v_rcp_f32_e32 v11, v11
	v_add_f32_e32 v10, 1.0, v10
	v_rcp_f32_e32 v10, v10
	s_waitcnt lgkmcnt(0)
	v_lshlrev_b32_e32 v9, 16, v102
	v_mul_f32_e32 v9, v11, v9
	v_add_f32_e32 v11, v192, v29
	v_mul_f32_e32 v11, 0xbfb8aa3b, v11
	v_exp_f32_e32 v11, v11
	v_mul_f32_e32 v10, v194, v10
	v_exp_f32_e32 v208, v10
	v_mul_f32_e32 v10, 0x3fb17218, v10
	v_fmamk_f32 v12, v10, 0x3c088888, v186
	v_fmaak_f32 v12, v10, v12, 0x3e2aaaab
	v_add_f32_e32 v11, 1.0, v11
	v_fma_f32 v12, v10, v12, 0.5
	v_rcp_f32_e32 v11, v11
	v_fma_f32 v12, v10, v12, 1.0
	v_mul_f32_e32 v12, v10, v12
	v_fma_f32 v13, v208, v208, -1.0
	v_cmp_lt_f32_e32 vcc, s76, v10
	v_mul_f32_e32 v11, v194, v11
	v_exp_f32_e32 v218, v11
	v_cndmask_b32_e32 v10, v13, v12, vcc
	v_add_f32_e32 v12, v191, v45
	v_mul_f32_e32 v12, 0xbfb8aa3b, v12
	v_mul_f32_e32 v11, 0x3fb17218, v11
	v_exp_f32_e32 v12, v12
	v_fmamk_f32 v14, v11, 0x3c088888, v186
	v_fmaak_f32 v14, v11, v14, 0x3e2aaaab
	v_fma_f32 v14, v11, v14, 0.5
	v_fma_f32 v14, v11, v14, 1.0
	v_sqrt_f32_e64 v10, -v10
	v_add_f32_e32 v12, 1.0, v12
	v_mul_f32_e32 v14, v11, v14
	v_fma_f32 v15, v218, v218, -1.0
	v_cmp_lt_f32_e32 vcc, s76, v11
	v_rcp_f32_e32 v12, v12
	v_mul_f32_e32 v227, v10, v9
	v_cndmask_b32_e32 v11, v15, v14, vcc
	v_sqrt_f32_e64 v11, -v11
	s_waitcnt lgkmcnt(0)
	v_lshlrev_b32_e32 v9, 16, v103
	v_mul_f32_e32 v9, v12, v9
	v_add_f32_e32 v10, v192, v30
	v_mul_f32_e32 v226, v11, v9
	v_add_f32_e32 v11, v191, v46
	v_mul_f32_e32 v11, 0xbfb8aa3b, v11
	v_exp_f32_e32 v11, v11
	v_mul_f32_e32 v10, 0xbfb8aa3b, v10
	v_exp_f32_e32 v10, v10
	v_add_f32_e32 v11, 1.0, v11
	v_rcp_f32_e32 v11, v11
	v_add_f32_e32 v10, 1.0, v10
	v_rcp_f32_e32 v10, v10
	s_waitcnt lgkmcnt(0)
	v_lshlrev_b32_e32 v9, 16, v104
	v_mul_f32_e32 v9, v11, v9
	v_add_f32_e32 v11, v192, v31
	v_mul_f32_e32 v11, 0xbfb8aa3b, v11
	v_exp_f32_e32 v11, v11
	v_mul_f32_e32 v10, v194, v10
	v_exp_f32_e32 v213, v10
	v_mul_f32_e32 v10, 0x3fb17218, v10
	v_fmamk_f32 v12, v10, 0x3c088888, v186
	v_fmaak_f32 v12, v10, v12, 0x3e2aaaab
	v_add_f32_e32 v11, 1.0, v11
	v_fma_f32 v12, v10, v12, 0.5
	v_rcp_f32_e32 v11, v11
	v_fma_f32 v12, v10, v12, 1.0
	v_mul_f32_e32 v12, v10, v12
	v_fma_f32 v13, v213, v213, -1.0
	v_cmp_lt_f32_e32 vcc, s76, v10
	v_mul_f32_e32 v11, v194, v11
	v_exp_f32_e32 v220, v11
	v_cndmask_b32_e32 v10, v13, v12, vcc
	v_add_f32_e32 v12, v191, v47
	v_mul_f32_e32 v12, 0xbfb8aa3b, v12
	v_mul_f32_e32 v11, 0x3fb17218, v11
	v_exp_f32_e32 v12, v12
	v_fmamk_f32 v14, v11, 0x3c088888, v186
	v_fmaak_f32 v14, v11, v14, 0x3e2aaaab
	v_fma_f32 v14, v11, v14, 0.5
	v_fma_f32 v14, v11, v14, 1.0
	v_sqrt_f32_e64 v10, -v10
	v_add_f32_e32 v12, 1.0, v12
	v_mul_f32_e32 v14, v11, v14
	v_fma_f32 v15, v220, v220, -1.0
	v_cmp_lt_f32_e32 vcc, s76, v11
	v_rcp_f32_e32 v12, v12
	v_mul_f32_e32 v224, v10, v9
	v_cndmask_b32_e32 v11, v15, v14, vcc
	v_sqrt_f32_e64 v11, -v11
	s_waitcnt lgkmcnt(0)
; __device__ __forceinline__ void scan_loadw(PP p, int dir, int n, int ct, int l31, int hl, ScanW& w) {
;     unsigned chv = (unsigned)(32 * ct + l31); asm volatile("" : "+v"(chv));
;     const unsigned ch = (unsigned)(dir * 512 + 64 * n) + chv;
;     w.ba = p->lru_b_a[ch]; w.bi = p->lru_b_i[ch];
;     w.sp8l2 = ((const float*)(p->ws + WS_SP8))[ch] * 1.4426950408889634f;
;     const bf16_t* wa_b = (const bf16_t*)(p->ws + WS_LRU) + (size_t)((dir * 2 + 0) * 8 + n) * 4096;
;     const bf16_t* wi_b = (const bf16_t*)(p->ws + WS_LRU) + (size_t)((dir * 2 + 1) * 8 + n) * 4096;
;     const unsigned lo = chv * 64u + 8u * (unsigned)hl;
; #pragma unroll
;     for (int st = 0; st < 4; ++st) { w.wfa[st] = *(const bf16x8*)(wa_b + lo + 16 * st); w.wfi[st] = *(const bf16x8*)(wi_b + lo + 16 * st); }
; template <int DIR>
; __device__ __forceinline__ void scan_dir(PP p, const bf16_t* xs, const ScanW& w, ScanW& wn, int ndir, int nct, bool do_next, int n, int ct, int l31, int hl, int id, int rowbase, bool latent, float (&hf)[2][16]) {
;     ...
;     for (int k = 0; k < 8; ++k) {
;         const int rt = k >> 2, g = k & 3;
;         float H = 0.f, A = 1.f;
; #pragma unroll
;         for (int jj = 0; jj < 4; ++jj) { const int j = DIR ? 3 - jj : jj; const float av = a[rt][4 * g + j]; H = av * H + u[rt][4 * g + j]; A *= av; }
;         Ao[k] = A; Ho[k] = H; Ap[k] = __shfl_xor(A, 32); Hp[k] = __shfl_xor(H, 32);
;     }
;     float Sin[8], Pin[8]; float Sx = 0.f, Px = 1.f;
; #pragma unroll
;     for (int kk = 0; kk < 8; ++kk) {
;         const int k = DIR ? 7 - kk : kk;
;         const float A0 = hl ? Ap[k] : Ao[k], H0 = hl ? Hp[k] : Ho[k], A1 = hl ? Ao[k] : Ap[k], H1 = hl ? Ho[k] : Hp[k];
;         float s0, p0, s1, p1;
;         if (DIR == 0) { s0 = Sx; p0 = Px; Sx = A0 * Sx + H0; Px *= A0; s1 = Sx; p1 = Px; Sx = A1 * Sx + H1; Px *= A1; }
;         else          { s1 = Sx; p1 = Px; Sx = A1 * Sx + H1; Px *= A1; s0 = Sx; p0 = Px; Sx = A0 * Sx + H0; Px *= A0; }
;         Sin[k] = hl ? s1 : s0; Pin[k] = hl ? p1 : p0;
;     }
;     asm volatile("" ::: "memory");
;     if (do_next) scan_loadw(p, ndir, n, nct, l31, hl, wn);
	v_lshlrev_b32_e32 v9, 16, v105
	v_mul_f32_e32 v9, v12, v9
	v_add_f32_e32 v10, v192, v32
	v_mul_f32_e32 v223, v11, v9
	v_add_f32_e32 v11, v191, v48
	v_mul_f32_e32 v11, 0xbfb8aa3b, v11
	v_exp_f32_e32 v11, v11
	v_mul_f32_e32 v10, 0xbfb8aa3b, v10
	v_exp_f32_e32 v10, v10
	v_add_f32_e32 v11, 1.0, v11
	v_rcp_f32_e32 v11, v11
	v_add_f32_e32 v10, 1.0, v10
	v_rcp_f32_e32 v10, v10
	s_waitcnt lgkmcnt(0)
	v_lshlrev_b32_e32 v9, 16, v106
	v_mul_f32_e32 v9, v11, v9
	v_add_f32_e32 v11, v192, v33
	v_mul_f32_e32 v11, 0xbfb8aa3b, v11
	v_exp_f32_e32 v11, v11
	v_mul_f32_e32 v10, v194, v10
	v_exp_f32_e32 v219, v10
	v_mul_f32_e32 v10, 0x3fb17218, v10
	v_fmamk_f32 v12, v10, 0x3c088888, v186
	v_fmaak_f32 v12, v10, v12, 0x3e2aaaab
	v_add_f32_e32 v11, 1.0, v11
	v_fma_f32 v12, v10, v12, 0.5
	v_rcp_f32_e32 v11, v11
	v_fma_f32 v12, v10, v12, 1.0
	v_mul_f32_e32 v12, v10, v12
	v_fma_f32 v13, v219, v219, -1.0
	v_cmp_lt_f32_e32 vcc, s76, v10
	v_mul_f32_e32 v11, v194, v11
	v_exp_f32_e32 v225, v11
	v_cndmask_b32_e32 v10, v13, v12, vcc
	v_add_f32_e32 v12, v191, v49
	v_mul_f32_e32 v12, 0xbfb8aa3b, v12
	v_mul_f32_e32 v11, 0x3fb17218, v11
	v_exp_f32_e32 v12, v12
	v_fmamk_f32 v13, v11, 0x3c088888, v186
	v_fmaak_f32 v13, v11, v13, 0x3e2aaaab
	v_fma_f32 v13, v11, v13, 0.5
	ds_read_u16 v0, v0 offset:61360
	v_fma_f32 v13, v11, v13, 1.0
	v_add_f32_e32 v12, 1.0, v12
	v_mul_f32_e32 v13, v11, v13
	v_fma_f32 v14, v225, v225, -1.0
	v_cmp_lt_f32_e32 vcc, s76, v11
	v_sqrt_f32_e64 v10, -v10
	v_rcp_f32_e32 v12, v12
	s_waitcnt lgkmcnt(0)
	v_lshlrev_b32_e32 v0, 16, v0
	v_cndmask_b32_e32 v11, v14, v13, vcc
	v_sqrt_f32_e64 v11, -v11
	v_mul_f32_e32 v229, v10, v9
	v_mul_f32_e32 v0, v12, v0
	v_and_b32_e32 v9, 64, v188
	v_mul_f32_e32 v228, v11, v0
	v_xor_b32_e32 v0, 32, v188
	v_add_u32_e32 v9, 64, v9
	v_cmp_lt_i32_e32 vcc, v0, v9
	v_fma_f32 v9, 0, v50, v2
	v_fma_f32 v9, v52, v9, v3
	v_fma_f32 v9, v51, v9, v4
	v_fma_f32 v34, v54, v9, v5
	v_fma_f32 v9, 0, v53, v6
	v_fma_f32 v9, v55, v9, v7
	v_fma_f32 v9, v67, v9, v8
	v_fma_f32 v255, v69, v9, v76
	v_fma_f32 v9, 0, v68, v74
	v_fma_f32 v9, v71, v9, v73
	v_mul_f32_e32 v10, v50, v52
	v_fma_f32 v9, v70, v9, v209
	v_mul_f32_e32 v10, v51, v10
	v_fma_f32 v251, v75, v9, v217
	v_fma_f32 v9, 0, v72, v197
	v_mul_f32_e32 v35, v54, v10
	v_mul_f32_e32 v10, v53, v55
	v_fma_f32 v9, v78, v9, v199
	v_mul_f32_e32 v10, v67, v10
	v_fma_f32 v9, v77, v9, v204
	v_mul_f32_e32 v154, v69, v10
	v_mul_f32_e32 v10, v68, v71
	v_fma_f32 v247, v79, v9, v202
	v_fma_f32 v9, 0, v80, v196
	v_mul_f32_e32 v10, v70, v10
	v_fma_f32 v9, v146, v9, v195
	v_mul_f32_e32 v253, v75, v10
	v_mul_f32_e32 v10, v72, v78
	v_fma_f32 v9, v81, v9, v214
	v_mul_f32_e32 v10, v77, v10
	v_fma_f32 v243, v198, v9, v211
	v_fma_f32 v9, 0, v147, v206
	v_mul_f32_e32 v249, v79, v10
	v_mul_f32_e32 v10, v80, v146
	v_fma_f32 v9, v201, v9, v205
	v_mul_f32_e32 v10, v81, v10
	v_fma_f32 v9, v200, v9, v222
	v_mul_f32_e32 v245, v198, v10
	v_mul_f32_e32 v10, v147, v201
	v_fma_f32 v239, v207, v9, v221
	v_fma_f32 v9, 0, v203, v216
	v_mul_f32_e32 v10, v200, v10
	v_fma_f32 v9, v210, v9, v215
	v_mul_f32_e32 v241, v207, v10
	v_mul_f32_e32 v10, v203, v210
	v_fma_f32 v9, v208, v9, v227
	v_mul_f32_e32 v10, v208, v10
	v_fma_f32 v234, v218, v9, v226
	v_fma_f32 v9, 0, v213, v224
	v_mul_f32_e32 v236, v218, v10
	v_fma_f32 v9, v220, v9, v223
	v_mul_f32_e32 v10, v213, v220
	v_cndmask_b32_e32 v0, v188, v0, vcc
	v_fma_f32 v9, v219, v9, v229
	v_mul_f32_e32 v10, v219, v10
	v_lshlrev_b32_e32 v0, 2, v0
	v_fma_f32 v230, v225, v9, v228
	v_mul_f32_e32 v231, v225, v10
	ds_bpermute_b32 v36, v0, v35
	ds_bpermute_b32 v37, v0, v34
	ds_bpermute_b32 v155, v0, v154
	ds_bpermute_b32 v212, v0, v255
	ds_bpermute_b32 v254, v0, v253
	ds_bpermute_b32 v252, v0, v251
	ds_bpermute_b32 v250, v0, v249
	ds_bpermute_b32 v248, v0, v247
	ds_bpermute_b32 v246, v0, v245
	ds_bpermute_b32 v244, v0, v243
	ds_bpermute_b32 v242, v0, v241
	ds_bpermute_b32 v240, v0, v239
	ds_bpermute_b32 v237, v0, v236
	ds_bpermute_b32 v235, v0, v234
	ds_bpermute_b32 v232, v0, v231
	ds_bpermute_b32 v233, v0, v230
	v_cndmask_b32_e64 v0, 0, 1, s[22:23]
	v_cmp_ne_u32_e64 s[4:5], 1, v0
	s_andn2_b64 vcc, exec, s[22:23]
	s_cbranch_vccnz .LBB0_380
	v_or_b32_e32 v9, s48, v148
	s_load_dwordx2 s[48:49], s[8:9], 0x58
	s_load_dwordx2 s[82:83], s[8:9], 0x68
	v_add_u32_e32 v0, s50, v9
	v_lshlrev_b64 v[10:11], 2, v[0:1]
	v_lshl_or_b32 v0, v9, 6, v149
	s_waitcnt lgkmcnt(0)
	v_lshl_add_u64 v[12:13], s[48:49], 0, v[10:11]
	global_load_dword v189, v[12:13], off
	v_lshl_add_u64 v[12:13], s[82:83], 0, v[10:11]
	global_load_dword v190, v[12:13], off
	v_lshl_add_u64 v[10:11], s[12:13], 0, v[10:11]
	v_lshlrev_b64 v[12:13], 1, v[0:1]
	v_lshl_add_u64 v[14:15], s[20:21], 0, v[12:13]
	v_lshl_add_u64 v[12:13], s[16:17], 0, v[12:13]
	global_load_dword v144, v[10:11], off
	global_load_dwordx4 v[82:85], v[14:15], off
	global_load_dwordx4 v[86:89], v[14:15], off offset:32
	global_load_dwordx4 v[90:93], v[14:15], off offset:64
	global_load_dwordx4 v[94:97], v[12:13], off offset:32
	global_load_dwordx4 v[102:105], v[12:13], off offset:64
	global_load_dwordx4 v[98:101], v[12:13], off
	global_load_dwordx4 v[106:109], v[14:15], off offset:96
	global_load_dwordx4 v[110:113], v[12:13], off offset:96

; __device__ __forceinline__ float bf2f(bf16_t b) { return __uint_as_float(((unsigned)b) << 16); }
; __device__ __forceinline__ float fast_sigmoid(float x) { return __builtin_amdgcn_rcpf(1.0f + __builtin_amdgcn_exp2f(-1.4426950408889634f * x)); }
; template <int DIR>
; __device__ __forceinline__ void scan_dir(PP p, const bf16_t* xs, const ScanW& w, ScanW& wn, int ndir, int nct, bool do_next, int n, int ct, int l31, int hl, int id, int rowbase, bool latent, float (&hf)[2][16]) {
;     ...
;         for (int st = 0; st < 4; ++st) af[st] = *(const bf16x8*)(xs + (32 * rt + l31) * XS + 64 * n + 16 * st + 8 * hl);
;         f32x16 ga, gi;
; #pragma unroll
;         for (int i = 0; i < 16; ++i) { ga[i] = 0.f; gi[i] = 0.f; }
; #pragma unroll
;         for (int st = 0; st < 4; ++st) { ga = __builtin_amdgcn_mfma_f32_32x32x16_bf16(af[st], wfa[st], ga, 0, 0, 0); gi = __builtin_amdgcn_mfma_f32_32x32x16_bf16(af[st], wfi[st], gi, 0, 0, 0); }
; #pragma unroll
;         for (int i = 0; i < 16; ++i) {
;             const int token = 32 * rt + 8 * (i >> 2) + 4 * hl + (i & 3);
;             const float xv = bf2f(xs[token * XS + ch]);
;             const float rr = fast_sigmoid(ga[i] + ba), ii = fast_sigmoid(gi[i] + bi);
;             const float la2 = rr * sp8l2;
;             const float av = __builtin_amdgcn_exp2f(la2);
;             const float t2 = la2 * 1.3862943611f;
;             float em1p = t2 * (1.0f + t2 * (0.5f + t2 * (0.16666667f + t2 * (0.041666668f + t2 * 0.0083333333f)))), em1e = __builtin_fmaf(av, av, -1.0f);
;             asm volatile("" : "+v"(em1p), "+v"(em1e));
;             const float em1 = (t2 > -0.1f) ? em1p : em1e;
;             a[rt][i] = av; u[rt][i] = __builtin_amdgcn_sqrtf(-em1) * (ii * xv);
;         }
.Lscan_nomul:
	v_mfma_f32_32x32x16_bf16 v[50:65], v[34:37], v[82:85], 0
	s_waitcnt vmcnt(2)
	v_mfma_f32_32x32x16_bf16 v[34:49], v[34:37], v[98:101], 0
	s_waitcnt lgkmcnt(1)
	v_mfma_f32_32x32x16_bf16 v[50:65], v[66:69], v[86:89], v[50:65]
	v_mfma_f32_32x32x16_bf16 v[34:49], v[66:69], v[94:97], v[34:49]
	ds_read_b128 v[66:69], v187 offset:96
	s_waitcnt lgkmcnt(1)
	v_mfma_f32_32x32x16_bf16 v[50:65], v[70:73], v[90:93], v[50:65]
	v_mfma_f32_32x32x16_bf16 v[34:49], v[70:73], v[102:105], v[34:49]
	s_waitcnt vmcnt(1) lgkmcnt(0)
	v_add_u32_e32 v145, v74, v185
	ds_read_u16 v114, v145
	ds_read_u16 v115, v145 offset:1040
	ds_read_u16 v116, v145 offset:2080
	ds_read_u16 v117, v213
	ds_read_u16 v118, v213 offset:1040
	ds_read_u16 v119, v213 offset:2080
	ds_read_u16 v120, v213 offset:3120
	ds_read_u16 v121, v213 offset:8320
	ds_read_u16 v122, v213 offset:9360
	ds_read_u16 v123, v213 offset:10400
	ds_read_u16 v124, v213 offset:24960
	ds_read_u16 v125, v213 offset:26000
	ds_read_u16 v126, v213 offset:27040
	ds_read_u16 v127, v213 offset:28080
	ds_read_u16 v128, v0 offset:41600
	ds_read_u16 v129, v0 offset:42640
	ds_read_u16 v130, v0 offset:43680
	ds_read_u16 v131, v0 offset:44720
	ds_read_u16 v132, v0 offset:49920
	ds_read_u16 v133, v0 offset:50960
	ds_read_u16 v134, v0 offset:52000
	ds_read_u16 v135, v0 offset:53040
	ds_read_u16 v136, v0 offset:58240
	ds_read_u16 v137, v0 offset:59280
	ds_read_u16 v138, v0 offset:60320
	v_mfma_f32_32x32x16_bf16 v[50:65], v[66:69], v[106:109], v[50:65]
	s_waitcnt vmcnt(0)
	v_mfma_f32_32x32x16_bf16 v[34:49], v[66:69], v[110:113], v[34:49]
	s_nop 9
	v_add_f32_e32 v50, v189, v50
	v_mul_f32_e32 v50, 0xbfb8aa3b, v50
	v_exp_f32_e32 v50, v50
	v_add_f32_e32 v51, v189, v51
	v_mul_f32_e32 v51, 0xbfb8aa3b, v51
	v_exp_f32_e32 v51, v51
	v_add_f32_e32 v50, 1.0, v50
	v_add_f32_e32 v34, v190, v34
	v_mul_f32_e32 v34, 0xbfb8aa3b, v34
	v_exp_f32_e32 v34, v34
	v_rcp_f32_e32 v50, v50
	v_add_f32_e32 v35, v190, v35
	v_mul_f32_e32 v35, 0xbfb8aa3b, v35
	v_add_f32_e32 v34, 1.0, v34
	v_mul_f32_e32 v50, v193, v50
	v_rcp_f32_e32 v67, v34
	v_exp_f32_e32 v34, v50
	v_mul_f32_e32 v50, 0x3fb17218, v50
	v_fmamk_f32 v68, v50, 0x3c088888, v186
	v_fmaak_f32 v68, v50, v68, 0x3e2aaaab
	v_exp_f32_e32 v35, v35
	v_add_f32_e32 v51, 1.0, v51
	v_fma_f32 v68, v50, v68, 0.5
	v_rcp_f32_e32 v51, v51
	v_fma_f32 v68, v50, v68, 1.0
	v_mul_f32_e32 v68, v50, v68
	v_fma_f32 v69, v34, v34, -1.0
	v_cmp_lt_f32_e32 vcc, s76, v50
	v_add_f32_e32 v35, 1.0, v35
	v_lshlrev_b32_e32 v66, 16, v75
	v_cndmask_b32_e32 v50, v69, v68, vcc
	v_rcp_f32_e32 v69, v35
	v_mul_f32_e32 v35, v193, v51
	v_exp_f32_e32 v147, v35
	v_mul_f32_e32 v35, 0x3fb17218, v35
	v_fmamk_f32 v51, v35, 0x3c088888, v186
	v_fmaak_f32 v51, v35, v51, 0x3e2aaaab
	v_mul_f32_e32 v66, v67, v66
	v_add_u32_e32 v67, v74, v185
	v_fma_f32 v51, v35, v51, 0.5
	v_fma_f32 v51, v35, v51, 1.0
	v_sqrt_f32_e64 v50, -v50
	v_mul_f32_e32 v51, v35, v51
	v_fma_f32 v70, v147, v147, -1.0
	v_cmp_lt_f32_e32 vcc, s76, v35
	v_add_f32_e32 v36, v190, v36
	v_mul_f32_e32 v36, 0xbfb8aa3b, v36
	v_cndmask_b32_e32 v35, v70, v51, vcc
	v_sqrt_f32_e64 v51, -v35
	v_exp_f32_e32 v36, v36
	v_mul_f32_e32 v35, v66, v50
	s_waitcnt lgkmcnt(0)
	v_lshlrev_b32_e32 v50, 16, v114
	v_mul_f32_e32 v50, v69, v50
	v_mul_f32_e32 v195, v50, v51
	v_add_f32_e32 v36, 1.0, v36
	v_rcp_f32_e32 v36, v36
	v_add_f32_e32 v51, v189, v52
	v_mul_f32_e32 v51, 0xbfb8aa3b, v51
	v_exp_f32_e32 v51, v51
	s_waitcnt lgkmcnt(0)
	v_lshlrev_b32_e32 v50, 16, v115
	v_mul_f32_e32 v36, v36, v50
	v_add_f32_e32 v50, v189, v53
	v_mul_f32_e32 v50, 0xbfb8aa3b, v50
	v_exp_f32_e32 v50, v50
	v_add_f32_e32 v51, 1.0, v51
	v_rcp_f32_e32 v51, v51
	v_add_f32_e32 v37, v190, v37
	v_add_f32_e32 v50, 1.0, v50
	v_rcp_f32_e32 v50, v50
	v_mul_f32_e32 v51, v193, v51
	v_exp_f32_e32 v196, v51
	v_mul_f32_e32 v51, 0x3fb17218, v51
	v_fmamk_f32 v52, v51, 0x3c088888, v186
	v_fmaak_f32 v52, v51, v52, 0x3e2aaaab
	v_mul_f32_e32 v50, v193, v50
	v_fma_f32 v52, v51, v52, 0.5
	v_mul_f32_e32 v37, 0xbfb8aa3b, v37
	v_exp_f32_e32 v198, v50
	v_mul_f32_e32 v50, 0x3fb17218, v50
	v_fma_f32 v52, v51, v52, 1.0
	v_exp_f32_e32 v37, v37
	v_fmamk_f32 v53, v50, 0x3c088888, v186
	v_mul_f32_e32 v52, v51, v52
	v_fma_f32 v66, v196, v196, -1.0
	v_fmaak_f32 v53, v50, v53, 0x3e2aaaab
	v_cmp_lt_f32_e32 vcc, s76, v51
	v_fma_f32 v53, v50, v53, 0.5
	v_fma_f32 v53, v50, v53, 1.0
	v_cndmask_b32_e32 v51, v66, v52, vcc
	v_sqrt_f32_e64 v51, -v51
	v_add_f32_e32 v37, 1.0, v37
	v_mul_f32_e32 v53, v50, v53
	v_fma_f32 v66, v198, v198, -1.0
	v_cmp_lt_f32_e32 vcc, s76, v50
	v_rcp_f32_e32 v37, v37
	v_mul_f32_e32 v197, v36, v51
	v_cndmask_b32_e32 v50, v66, v53, vcc
	v_sqrt_f32_e64 v50, -v50
	s_waitcnt lgkmcnt(0)
	v_lshlrev_b32_e32 v36, 16, v116
	v_mul_f32_e32 v36, v37, v36
	v_add_f32_e32 v38, v190, v38
	v_mul_f32_e32 v199, v50, v36
	v_mul_f32_e32 v38, 0xbfb8aa3b, v38
	v_exp_f32_e32 v38, v38
	v_add_f32_e32 v37, v189, v54
	v_mul_f32_e32 v37, 0xbfb8aa3b, v37
	v_exp_f32_e32 v37, v37
	s_waitcnt lgkmcnt(0)
	v_lshlrev_b32_e32 v50, 16, v117
	v_add_f32_e32 v36, 1.0, v38
	v_rcp_f32_e32 v38, v36
	v_add_f32_e32 v37, 1.0, v37
	v_rcp_f32_e32 v37, v37
	v_add_f32_e32 v39, v190, v39
	v_mul_f32_e32 v50, v38, v50
	v_add_f32_e32 v38, v189, v55
	v_mul_f32_e32 v38, 0xbfb8aa3b, v38
	v_exp_f32_e32 v38, v38
	v_mul_f32_e32 v37, v193, v37
	v_exp_f32_e32 v36, v37
	v_mul_f32_e32 v37, 0x3fb17218, v37
	v_fmamk_f32 v51, v37, 0x3c088888, v186
	v_fmaak_f32 v51, v37, v51, 0x3e2aaaab
	v_add_f32_e32 v38, 1.0, v38
	v_fma_f32 v51, v37, v51, 0.5
	v_rcp_f32_e32 v38, v38
	v_fma_f32 v51, v37, v51, 1.0
	v_mul_f32_e32 v39, 0xbfb8aa3b, v39
	v_mul_f32_e32 v51, v37, v51
	v_fma_f32 v52, v36, v36, -1.0
	v_exp_f32_e32 v39, v39
	v_cmp_lt_f32_e32 vcc, s76, v37
	v_add_f32_e32 v40, v190, v40
	v_add_f32_e32 v39, 1.0, v39
	v_cndmask_b32_e32 v37, v52, v51, vcc
	v_mul_f32_e32 v52, v193, v38
	v_exp_f32_e32 v38, v52
	v_mul_f32_e32 v52, 0x3fb17218, v52
	v_sqrt_f32_e64 v37, -v37
	v_fmamk_f32 v53, v52, 0x3c088888, v186
	v_rcp_f32_e32 v39, v39
	v_fmaak_f32 v53, v52, v53, 0x3e2aaaab
	v_mul_f32_e32 v40, 0xbfb8aa3b, v40
	v_fma_f32 v53, v52, v53, 0.5
	v_exp_f32_e32 v40, v40
	v_fma_f32 v53, v52, v53, 1.0
	v_mul_f32_e32 v53, v52, v53
	v_fma_f32 v54, v38, v38, -1.0
	v_mul_f32_e32 v37, v37, v50
	s_waitcnt lgkmcnt(0)
; __device__ __forceinline__ float bf2f(bf16_t b) { return __uint_as_float(((unsigned)b) << 16); }
; __device__ __forceinline__ float fast_sigmoid(float x) { return __builtin_amdgcn_rcpf(1.0f + __builtin_amdgcn_exp2f(-1.4426950408889634f * x)); }
; template <int DIR>
; __device__ __forceinline__ void scan_dir(PP p, const bf16_t* xs, const ScanW& w, ScanW& wn, int ndir, int nct, bool do_next, int n, int ct, int l31, int hl, int id, int rowbase, bool latent, float (&hf)[2][16]) {
;     ...
; #pragma unroll
;         for (int i = 0; i < 16; ++i) {
;             const int token = 32 * rt + 8 * (i >> 2) + 4 * hl + (i & 3);
;             const float xv = bf2f(xs[token * XS + ch]);
;             const float rr = fast_sigmoid(ga[i] + ba), ii = fast_sigmoid(gi[i] + bi);
;             const float la2 = rr * sp8l2;
;             const float av = __builtin_amdgcn_exp2f(la2);
;             const float t2 = la2 * 1.3862943611f;
;             float em1p = t2 * (1.0f + t2 * (0.5f + t2 * (0.16666667f + t2 * (0.041666668f + t2 * 0.0083333333f)))), em1e = __builtin_fmaf(av, av, -1.0f);
;             asm volatile("" : "+v"(em1p), "+v"(em1e));
;             const float em1 = (t2 > -0.1f) ? em1p : em1e;
;             a[rt][i] = av; u[rt][i] = __builtin_amdgcn_sqrtf(-em1) * (ii * xv);
;         }
	v_lshlrev_b32_e32 v50, 16, v118
	v_mul_f32_e32 v39, v39, v50
	v_add_f32_e32 v51, v189, v56
	v_mul_f32_e32 v51, 0xbfb8aa3b, v51
	v_add_f32_e32 v40, 1.0, v40
	v_exp_f32_e32 v51, v51
	v_rcp_f32_e32 v40, v40
	s_waitcnt lgkmcnt(0)
	v_lshlrev_b32_e32 v50, 16, v119
	v_cmp_lt_f32_e32 vcc, s76, v52
	v_add_f32_e32 v51, 1.0, v51
	v_mul_f32_e32 v40, v40, v50
	v_add_f32_e32 v50, v189, v57
	v_rcp_f32_e32 v51, v51
	v_mul_f32_e32 v50, 0xbfb8aa3b, v50
	v_cndmask_b32_e32 v52, v54, v53, vcc
	v_exp_f32_e32 v50, v50
	v_sqrt_f32_e64 v52, -v52
	v_mul_f32_e32 v51, v193, v51
	v_exp_f32_e32 v200, v51
	v_mul_f32_e32 v51, 0x3fb17218, v51
	v_add_f32_e32 v50, 1.0, v50
	v_mul_f32_e32 v39, v52, v39
	v_fmamk_f32 v52, v51, 0x3c088888, v186
	v_rcp_f32_e32 v50, v50
	v_fmaak_f32 v52, v51, v52, 0x3e2aaaab
	v_add_f32_e32 v41, v190, v41
	v_fma_f32 v52, v51, v52, 0.5
	v_mul_f32_e32 v41, 0xbfb8aa3b, v41
	v_fma_f32 v52, v51, v52, 1.0
	v_exp_f32_e32 v41, v41
	v_mul_f32_e32 v52, v51, v52
	v_fma_f32 v53, v200, v200, -1.0
	v_mul_f32_e32 v50, v193, v50
	v_cmp_lt_f32_e32 vcc, s76, v51
	v_exp_f32_e32 v202, v50
	v_mul_f32_e32 v50, 0x3fb17218, v50
	v_cndmask_b32_e32 v51, v53, v52, vcc
	v_fmamk_f32 v53, v50, 0x3c088888, v186
	v_sqrt_f32_e64 v51, -v51
	v_add_f32_e32 v41, 1.0, v41
	v_fmaak_f32 v53, v50, v53, 0x3e2aaaab
	v_rcp_f32_e32 v41, v41
	v_fma_f32 v53, v50, v53, 0.5
	v_fma_f32 v53, v50, v53, 1.0
	v_mul_f32_e32 v53, v50, v53
	v_fma_f32 v54, v202, v202, -1.0
	v_cmp_lt_f32_e32 vcc, s76, v50
	v_mul_f32_e32 v201, v51, v40
	s_waitcnt lgkmcnt(0)
	v_lshlrev_b32_e32 v40, 16, v120
	v_cndmask_b32_e32 v50, v54, v53, vcc
	v_sqrt_f32_e64 v50, -v50
	v_mul_f32_e32 v40, v41, v40
	v_add_f32_e32 v41, v189, v58
	v_mul_f32_e32 v41, 0xbfb8aa3b, v41
	v_exp_f32_e32 v41, v41
	v_add_f32_e32 v42, v190, v42
	v_mul_f32_e32 v203, v50, v40
	v_mul_f32_e32 v42, 0xbfb8aa3b, v42
	v_exp_f32_e32 v42, v42
	v_add_f32_e32 v41, 1.0, v41
	v_rcp_f32_e32 v41, v41
	s_waitcnt lgkmcnt(0)
	v_lshlrev_b32_e32 v50, 16, v121
	v_add_f32_e32 v40, 1.0, v42
	v_rcp_f32_e32 v42, v40
	v_mul_f32_e32 v41, v193, v41
	v_exp_f32_e32 v40, v41
	v_mul_f32_e32 v41, 0x3fb17218, v41
	v_fmamk_f32 v51, v41, 0x3c088888, v186
	v_fmaak_f32 v51, v41, v51, 0x3e2aaaab
	v_mul_f32_e32 v50, v42, v50
	v_add_f32_e32 v42, v189, v59
	v_fma_f32 v51, v41, v51, 0.5
	v_mul_f32_e32 v42, 0xbfb8aa3b, v42
	v_fma_f32 v51, v41, v51, 1.0
	v_exp_f32_e32 v42, v42
	v_mul_f32_e32 v51, v41, v51
	v_fma_f32 v52, v40, v40, -1.0
	v_cmp_lt_f32_e32 vcc, s76, v41
	v_add_f32_e32 v42, 1.0, v42
	v_rcp_f32_e32 v42, v42
	v_cndmask_b32_e32 v41, v52, v51, vcc
	v_sqrt_f32_e64 v41, -v41
	v_add_f32_e32 v43, v190, v43
	v_mul_f32_e32 v52, v193, v42
	v_mul_f32_e32 v43, 0xbfb8aa3b, v43
	v_mul_f32_e32 v41, v41, v50
	s_waitcnt lgkmcnt(0)
	v_lshlrev_b32_e32 v50, 16, v122
	v_add_f32_e32 v51, v189, v60
	v_mul_f32_e32 v51, 0xbfb8aa3b, v51
	v_exp_f32_e32 v42, v52
	v_mul_f32_e32 v52, 0x3fb17218, v52
	v_exp_f32_e32 v51, v51
	v_exp_f32_e32 v43, v43
	v_fmamk_f32 v53, v52, 0x3c088888, v186
	v_fmaak_f32 v53, v52, v53, 0x3e2aaaab
	v_fma_f32 v53, v52, v53, 0.5
	v_fma_f32 v53, v52, v53, 1.0
	v_add_f32_e32 v51, 1.0, v51
	v_add_f32_e32 v43, 1.0, v43
	v_mul_f32_e32 v53, v52, v53
	v_fma_f32 v54, v42, v42, -1.0
	v_cmp_lt_f32_e32 vcc, s76, v52
	v_rcp_f32_e32 v51, v51
	v_rcp_f32_e32 v43, v43
	v_add_f32_e32 v44, v190, v44
	v_cndmask_b32_e32 v52, v54, v53, vcc
	v_sqrt_f32_e64 v52, -v52
	v_mul_f32_e32 v51, v193, v51
	v_mul_f32_e32 v43, v43, v50
	v_exp_f32_e32 v204, v51
	v_mul_f32_e32 v51, 0x3fb17218, v51
	v_mul_f32_e32 v43, v52, v43
	v_fmamk_f32 v52, v51, 0x3c088888, v186
	v_fmaak_f32 v52, v51, v52, 0x3e2aaaab
	v_mul_f32_e32 v44, 0xbfb8aa3b, v44
	v_fma_f32 v52, v51, v52, 0.5
	v_exp_f32_e32 v44, v44
	v_fma_f32 v52, v51, v52, 1.0
	v_mul_f32_e32 v52, v51, v52
	v_fma_f32 v53, v204, v204, -1.0
	v_cmp_lt_f32_e32 vcc, s76, v51
	v_add_f32_e32 v44, 1.0, v44
	v_rcp_f32_e32 v44, v44
	v_cndmask_b32_e32 v51, v53, v52, vcc
	v_add_f32_e32 v52, v189, v61
	v_mul_f32_e32 v52, 0xbfb8aa3b, v52
	v_exp_f32_e32 v52, v52
	s_waitcnt lgkmcnt(0)
	v_lshlrev_b32_e32 v50, 16, v123
	v_mul_f32_e32 v50, v44, v50
	v_add_f32_e32 v45, v190, v45
	v_add_f32_e32 v44, 1.0, v52
	v_rcp_f32_e32 v44, v44
	v_mul_f32_e32 v45, 0xbfb8aa3b, v45
	v_exp_f32_e32 v52, v45
	v_add_f32_e32 v45, v189, v62
	v_mul_f32_e32 v44, v193, v44
	v_mul_f32_e32 v54, 0x3fb17218, v44
	v_mul_f32_e32 v45, 0xbfb8aa3b, v45
	v_exp_f32_e32 v205, v44
	v_fmamk_f32 v44, v54, 0x3c088888, v186
	v_exp_f32_e32 v45, v45
	v_fmaak_f32 v44, v54, v44, 0x3e2aaaab
	v_fma_f32 v44, v54, v44, 0.5
	v_fma_f32 v44, v54, v44, 1.0
	v_mul_f32_e32 v55, v54, v44
	v_add_f32_e32 v44, 1.0, v45
	v_rcp_f32_e32 v44, v44
	v_add_f32_e32 v57, v189, v63
	v_mul_f32_e32 v57, 0xbfb8aa3b, v57
	v_exp_f32_e32 v57, v57
	v_mul_f32_e32 v45, v193, v44
	v_mul_f32_e32 v154, 0x3fb17218, v45
	v_exp_f32_e32 v44, v45
	v_fmamk_f32 v45, v154, 0x3c088888, v186
	v_fmaak_f32 v45, v154, v45, 0x3e2aaaab
	v_fma_f32 v45, v154, v45, 0.5
	v_fma_f32 v45, v154, v45, 1.0
	v_mul_f32_e32 v155, v154, v45
	v_add_f32_e32 v45, 1.0, v57
	v_rcp_f32_e32 v45, v45
	v_add_f32_e32 v58, v189, v64
	v_mul_f32_e32 v58, 0xbfb8aa3b, v58
	v_exp_f32_e32 v58, v58
	v_mul_f32_e32 v57, v193, v45
	v_mul_f32_e32 v159, 0x3fb17218, v57
	v_exp_f32_e32 v45, v57
	v_fmamk_f32 v57, v159, 0x3c088888, v186
	v_fmaak_f32 v57, v159, v57, 0x3e2aaaab
	v_fma_f32 v57, v159, v57, 0.5
	v_fma_f32 v57, v159, v57, 1.0
	v_mul_f32_e32 v209, v159, v57
	v_add_f32_e32 v57, 1.0, v58
	v_rcp_f32_e32 v57, v57
	v_add_f32_e32 v58, v189, v65
	v_mul_f32_e32 v58, 0xbfb8aa3b, v58
	v_exp_f32_e32 v58, v58
	v_mul_f32_e32 v57, v193, v57
	v_mul_f32_e32 v222, 0x3fb17218, v57
	v_exp_f32_e32 v206, v57
	v_fmamk_f32 v57, v222, 0x3c088888, v186
	v_fmaak_f32 v57, v222, v57, 0x3e2aaaab
	v_fma_f32 v57, v222, v57, 0.5
	v_fma_f32 v57, v222, v57, 1.0
	v_mul_f32_e32 v223, v222, v57
	v_add_f32_e32 v57, 1.0, v58
	v_rcp_f32_e32 v57, v57
	v_sqrt_f32_e64 v51, -v51
	v_fma_f32 v56, v205, v205, -1.0
	v_fma_f32 v156, v44, v44, -1.0
	v_mul_f32_e32 v57, v193, v57
	v_mul_f32_e32 v226, 0x3fb17218, v57
	v_exp_f32_e32 v207, v57
	v_fmamk_f32 v57, v226, 0x3c088888, v186
	v_fmaak_f32 v57, v226, v57, 0x3e2aaaab
	v_fma_f32 v57, v226, v57, 0.5
	v_fma_f32 v57, v226, v57, 1.0
	v_fma_f32 v210, v45, v45, -1.0
	v_fma_f32 v224, v206, v206, -1.0
	v_mul_f32_e32 v227, v226, v57
	v_fma_f32 v228, v207, v207, -1.0
	ds_read_u16 v53, v213 offset:11440
	ds_read_u16 v70, v213 offset:16640
	ds_read_u16 v158, v213 offset:17680
	ds_read_u16 v212, v213 offset:18720
	ds_read_u16 v225, v213 offset:19760
	ds_read_b128 v[66:69], v187 offset:33280
	ds_read_b128 v[214:217], v187 offset:33312
	v_mul_f32_e32 v208, v51, v50
	v_add_f32_e32 v50, 1.0, v52
	v_cmp_lt_f32_e32 vcc, s76, v54
	v_rcp_f32_e32 v72, v50
	s_waitcnt lgkmcnt(6)
; __device__ __forceinline__ float bf2f(bf16_t b) { return __uint_as_float(((unsigned)b) << 16); }
; __device__ __forceinline__ float fast_sigmoid(float x) { return __builtin_amdgcn_rcpf(1.0f + __builtin_amdgcn_exp2f(-1.4426950408889634f * x)); }
; template <int DIR>
; __device__ __forceinline__ void scan_dir(PP p, const bf16_t* xs, const ScanW& w, ScanW& wn, int ndir, int nct, bool do_next, int n, int ct, int l31, int hl, int id, int rowbase, bool latent, float (&hf)[2][16]) {
;     ...
;         bf16x8 af[4];
; #pragma unroll
;         for (int st = 0; st < 4; ++st) af[st] = *(const bf16x8*)(xs + (32 * rt + l31) * XS + 64 * n + 16 * st + 8 * hl);
;         f32x16 ga, gi;
; #pragma unroll
;         for (int i = 0; i < 16; ++i) { ga[i] = 0.f; gi[i] = 0.f; }
; #pragma unroll
;         for (int st = 0; st < 4; ++st) { ga = __builtin_amdgcn_mfma_f32_32x32x16_bf16(af[st], wfa[st], ga, 0, 0, 0); gi = __builtin_amdgcn_mfma_f32_32x32x16_bf16(af[st], wfi[st], gi, 0, 0, 0); }
; #pragma unroll
;         for (int i = 0; i < 16; ++i) {
;             const int token = 32 * rt + 8 * (i >> 2) + 4 * hl + (i & 3);
;             const float xv = bf2f(xs[token * XS + ch]);
;             const float rr = fast_sigmoid(ga[i] + ba), ii = fast_sigmoid(gi[i] + bi);
;             const float la2 = rr * sp8l2;
;             const float av = __builtin_amdgcn_exp2f(la2);
;             const float t2 = la2 * 1.3862943611f;
;             float em1p = t2 * (1.0f + t2 * (0.5f + t2 * (0.16666667f + t2 * (0.041666668f + t2 * 0.0083333333f)))), em1e = __builtin_fmaf(av, av, -1.0f);
;             asm volatile("" : "+v"(em1p), "+v"(em1e));
;             const float em1 = (t2 > -0.1f) ? em1p : em1e;
;             a[rt][i] = av; u[rt][i] = __builtin_amdgcn_sqrtf(-em1) * (ii * xv);
;         }
	v_lshlrev_b32_e32 v71, 16, v53
	v_cndmask_b32_e32 v50, v56, v55, vcc
	v_sqrt_f32_e64 v73, -v50
	v_mul_f32_e32 v71, v72, v71
	s_waitcnt lgkmcnt(1)
	v_mfma_f32_32x32x16_bf16 v[50:65], v[66:69], v[82:85], 0
	v_lshlrev_b32_e32 v230, 16, v70
	v_mul_f32_e32 v211, v73, v71
	v_add_f32_e32 v46, v190, v46
	v_mul_f32_e32 v46, 0xbfb8aa3b, v46
	v_exp_f32_e32 v46, v46
	ds_read_b128 v[218:221], v187 offset:33344
	v_cmp_lt_f32_e32 vcc, s76, v154
	v_mfma_f32_32x32x16_bf16 v[66:81], v[66:69], v[98:101], 0
	v_add_f32_e32 v46, 1.0, v46
	v_add_f32_e32 v47, v190, v47
	v_rcp_f32_e32 v46, v46
	v_cndmask_b32_e32 v154, v156, v155, vcc
	v_mul_f32_e32 v47, 0xbfb8aa3b, v47
	v_sqrt_f32_e64 v154, -v154
	v_exp_f32_e32 v155, v47
	s_waitcnt lgkmcnt(1)
	v_mfma_f32_32x32x16_bf16 v[66:81], v[214:217], v[94:97], v[66:81]
	v_mul_f32_e32 v46, v46, v230
	v_mul_f32_e32 v47, v154, v46
	v_add_f32_e32 v154, 1.0, v155
	v_rcp_f32_e32 v154, v154
	v_add_f32_e32 v48, v190, v48
	v_lshlrev_b32_e32 v46, 16, v158
	v_cmp_lt_f32_e32 vcc, s76, v159
	v_mfma_f32_32x32x16_bf16 v[50:65], v[214:217], v[86:89], v[50:65]
	ds_read_b128 v[214:217], v187 offset:33376
	v_mul_f32_e32 v48, 0xbfb8aa3b, v48
	v_cndmask_b32_e32 v155, v210, v209, vcc
	v_mul_f32_e32 v46, v154, v46
	v_exp_f32_e32 v154, v48
	v_add_f32_e32 v49, v190, v49
	v_sqrt_f32_e64 v155, -v155
	s_waitcnt lgkmcnt(1)
	v_mfma_f32_32x32x16_bf16 v[66:81], v[218:221], v[102:105], v[66:81]
	v_mul_f32_e32 v49, 0xbfb8aa3b, v49
	v_exp_f32_e32 v49, v49
	v_add_f32_e32 v154, 1.0, v154
	v_cmp_lt_f32_e32 vcc, s76, v222
	v_mul_f32_e32 v48, v155, v46
	v_rcp_f32_e32 v154, v154
	v_cndmask_b32_e32 v155, v224, v223, vcc
	v_mfma_f32_32x32x16_bf16 v[50:65], v[218:221], v[90:93], v[50:65]
	v_sqrt_f32_e64 v155, -v155
	v_add_f32_e32 v49, 1.0, v49
	v_rcp_f32_e32 v49, v49
	v_lshlrev_b32_e32 v46, 16, v212
	v_cmp_lt_f32_e32 vcc, s76, v226
	v_mul_f32_e32 v46, v154, v46
	v_mul_f32_e32 v209, v155, v46
	s_waitcnt lgkmcnt(0)
	v_mfma_f32_32x32x16_bf16 v[66:81], v[214:217], v[110:113], v[66:81]
	v_cndmask_b32_e32 v154, v228, v227, vcc
	v_sqrt_f32_e64 v154, -v154
	v_lshlrev_b32_e32 v46, 16, v225
	v_mul_f32_e32 v46, v49, v46
	v_mul_f32_e32 v210, v154, v46
	v_mul_f32_e32 v158, v205, v204
	v_mfma_f32_32x32x16_bf16 v[50:65], v[214:217], v[106:109], v[50:65]
	s_nop 3
	v_add_f32_e32 v49, v190, v66
	v_mul_f32_e32 v49, 0xbfb8aa3b, v49
	v_exp_f32_e32 v49, v49
	v_mul_f32_e32 v158, v42, v158
	v_mul_f32_e32 v217, v40, v158
	v_mul_f32_e32 v158, v207, v206
	v_add_f32_e32 v49, 1.0, v49
	s_nop 0
	v_add_f32_e32 v46, v189, v50
	v_mul_f32_e32 v46, 0xbfb8aa3b, v46
	v_exp_f32_e32 v46, v46
	v_rcp_f32_e32 v49, v49
	s_waitcnt lgkmcnt(0)
	v_lshlrev_b32_e32 v50, 16, v124
	v_add_f32_e32 v52, v189, v52
	v_add_f32_e32 v46, 1.0, v46
	v_rcp_f32_e32 v46, v46
	v_mul_f32_e32 v49, v49, v50
	v_add_f32_e32 v50, v189, v51
	v_mul_f32_e32 v50, 0xbfb8aa3b, v50
	v_exp_f32_e32 v50, v50
	v_mul_f32_e32 v66, v193, v46
	v_exp_f32_e32 v46, v66
	v_mul_f32_e32 v66, 0x3fb17218, v66
	v_fmamk_f32 v154, v66, 0x3c088888, v186
	v_fmaak_f32 v154, v66, v154, 0x3e2aaaab
	v_add_f32_e32 v50, 1.0, v50
	v_fma_f32 v154, v66, v154, 0.5
	v_add_f32_e32 v51, v190, v67
	v_rcp_f32_e32 v50, v50
	v_fma_f32 v154, v66, v154, 1.0
	v_mul_f32_e32 v51, 0xbfb8aa3b, v51
	v_mul_f32_e32 v154, v66, v154
	v_fma_f32 v155, v46, v46, -1.0
	v_exp_f32_e32 v51, v51
	v_cmp_lt_f32_e32 vcc, s76, v66
	v_add_f32_e32 v51, 1.0, v51
	v_cndmask_b32_e32 v66, v155, v154, vcc
	v_mul_f32_e32 v154, v193, v50
	v_exp_f32_e32 v50, v154
	v_mul_f32_e32 v154, 0x3fb17218, v154
	v_sqrt_f32_e64 v66, -v66
	v_fmamk_f32 v155, v154, 0x3c088888, v186
	v_rcp_f32_e32 v51, v51
	v_fmaak_f32 v155, v154, v155, 0x3e2aaaab
	v_fma_f32 v155, v154, v155, 0.5
	v_fma_f32 v155, v154, v155, 1.0
	v_mul_f32_e32 v155, v154, v155
	v_fma_f32 v156, v50, v50, -1.0
	v_mul_f32_e32 v49, v49, v66
	s_waitcnt lgkmcnt(0)
	v_lshlrev_b32_e32 v66, 16, v125
	v_mul_f32_e32 v52, 0xbfb8aa3b, v52
	v_add_f32_e32 v67, v190, v68
	v_mul_f32_e32 v51, v51, v66
	v_exp_f32_e32 v52, v52
	v_mul_f32_e32 v67, 0xbfb8aa3b, v67
	v_exp_f32_e32 v67, v67
	v_cmp_lt_f32_e32 vcc, s76, v154
	v_add_f32_e32 v52, 1.0, v52
	v_rcp_f32_e32 v52, v52
	s_waitcnt lgkmcnt(0)
	v_lshlrev_b32_e32 v68, 16, v126
	v_add_f32_e32 v66, 1.0, v67
	v_add_f32_e32 v53, v189, v53
	v_cndmask_b32_e32 v154, v156, v155, vcc
	v_rcp_f32_e32 v67, v66
	v_mul_f32_e32 v53, 0xbfb8aa3b, v53
	v_sqrt_f32_e64 v154, -v154
	v_exp_f32_e32 v53, v53
	v_mul_f32_e32 v52, v193, v52
	v_exp_f32_e32 v66, v52
	v_mul_f32_e32 v52, 0x3fb17218, v52
	v_mul_f32_e32 v67, v67, v68
	v_add_f32_e32 v68, v190, v69
	v_mul_f32_e32 v51, v51, v154
	v_fmamk_f32 v154, v52, 0x3c088888, v186
	v_mul_f32_e32 v68, 0xbfb8aa3b, v68
	v_add_f32_e32 v53, 1.0, v53
	v_fmaak_f32 v154, v52, v154, 0x3e2aaaab
	v_exp_f32_e32 v68, v68
	v_rcp_f32_e32 v53, v53
	v_fma_f32 v154, v52, v154, 0.5
	v_fma_f32 v154, v52, v154, 1.0
	v_mul_f32_e32 v154, v52, v154
	v_fma_f32 v155, v66, v66, -1.0
	v_cmp_lt_f32_e32 vcc, s76, v52
	v_add_f32_e32 v68, 1.0, v68
	v_mul_f32_e32 v53, v193, v53
	v_cndmask_b32_e32 v52, v155, v154, vcc
	v_rcp_f32_e32 v154, v68
	v_exp_f32_e32 v68, v53
	v_mul_f32_e32 v53, 0x3fb17218, v53
	v_fmamk_f32 v155, v53, 0x3c088888, v186
	v_fmaak_f32 v155, v53, v155, 0x3e2aaaab
	v_fma_f32 v155, v53, v155, 0.5
	v_fma_f32 v155, v53, v155, 1.0
	v_sqrt_f32_e64 v52, -v52
	v_mul_f32_e32 v155, v53, v155
	v_fma_f32 v156, v68, v68, -1.0
	v_cmp_lt_f32_e32 vcc, s76, v53
	v_mul_f32_e32 v67, v67, v52
	s_waitcnt lgkmcnt(0)
	v_lshlrev_b32_e32 v52, 16, v127
	v_cndmask_b32_e32 v53, v156, v155, vcc
	v_sqrt_f32_e64 v53, -v53
	v_mul_f32_e32 v52, v154, v52
	v_add_f32_e32 v56, v189, v56
	v_mul_f32_e32 v56, 0xbfb8aa3b, v56
	v_mul_f32_e32 v69, v53, v52
	v_add_f32_e32 v53, v189, v54
	v_add_f32_e32 v54, v190, v70
	v_mul_f32_e32 v54, 0xbfb8aa3b, v54
	v_exp_f32_e32 v54, v54
	v_mul_f32_e32 v53, 0xbfb8aa3b, v53
	v_exp_f32_e32 v53, v53
	s_waitcnt lgkmcnt(0)
; __device__ __forceinline__ float bf2f(bf16_t b) { return __uint_as_float(((unsigned)b) << 16); }
; __device__ __forceinline__ float fast_sigmoid(float x) { return __builtin_amdgcn_rcpf(1.0f + __builtin_amdgcn_exp2f(-1.4426950408889634f * x)); }
; template <int DIR>
; __device__ __forceinline__ void scan_dir(PP p, const bf16_t* xs, const ScanW& w, ScanW& wn, int ndir, int nct, bool do_next, int n, int ct, int l31, int hl, int id, int rowbase, bool latent, float (&hf)[2][16]) {
;     ...
;         for (int i = 0; i < 16; ++i) {
;             const int token = 32 * rt + 8 * (i >> 2) + 4 * hl + (i & 3);
;             const float xv = bf2f(xs[token * XS + ch]);
;             const float rr = fast_sigmoid(ga[i] + ba), ii = fast_sigmoid(gi[i] + bi);
;             const float la2 = rr * sp8l2;
;             const float av = __builtin_amdgcn_exp2f(la2);
;             const float t2 = la2 * 1.3862943611f;
;             float em1p = t2 * (1.0f + t2 * (0.5f + t2 * (0.16666667f + t2 * (0.041666668f + t2 * 0.0083333333f)))), em1e = __builtin_fmaf(av, av, -1.0f);
;             asm volatile("" : "+v"(em1p), "+v"(em1e));
;             const float em1 = (t2 > -0.1f) ? em1p : em1e;
;             a[rt][i] = av; u[rt][i] = __builtin_amdgcn_sqrtf(-em1) * (ii * xv);
;         }
	v_lshlrev_b32_e32 v70, 16, v128
	v_add_f32_e32 v52, 1.0, v54
	v_rcp_f32_e32 v54, v52
	v_add_f32_e32 v53, 1.0, v53
	v_rcp_f32_e32 v53, v53
	v_exp_f32_e32 v56, v56
	v_mul_f32_e32 v70, v54, v70
	v_add_f32_e32 v54, v189, v55
	v_mul_f32_e32 v54, 0xbfb8aa3b, v54
	v_exp_f32_e32 v54, v54
	v_mul_f32_e32 v53, v193, v53
	v_exp_f32_e32 v52, v53
	v_mul_f32_e32 v53, 0x3fb17218, v53
	v_fmamk_f32 v154, v53, 0x3c088888, v186
	v_fmaak_f32 v154, v53, v154, 0x3e2aaaab
	v_add_f32_e32 v54, 1.0, v54
	v_fma_f32 v154, v53, v154, 0.5
	v_add_f32_e32 v55, v190, v71
	v_rcp_f32_e32 v54, v54
	v_fma_f32 v154, v53, v154, 1.0
	v_mul_f32_e32 v55, 0xbfb8aa3b, v55
	v_mul_f32_e32 v154, v53, v154
	v_fma_f32 v155, v52, v52, -1.0
	v_exp_f32_e32 v55, v55
	v_cmp_lt_f32_e32 vcc, s76, v53
	v_add_f32_e32 v55, 1.0, v55
	v_cndmask_b32_e32 v53, v155, v154, vcc
	v_mul_f32_e32 v154, v193, v54
	v_exp_f32_e32 v54, v154
	v_mul_f32_e32 v154, 0x3fb17218, v154
	v_sqrt_f32_e64 v53, -v53
	v_fmamk_f32 v155, v154, 0x3c088888, v186
	v_rcp_f32_e32 v55, v55
	v_fmaak_f32 v155, v154, v155, 0x3e2aaaab
	v_fma_f32 v155, v154, v155, 0.5
	v_fma_f32 v155, v154, v155, 1.0
	v_mul_f32_e32 v155, v154, v155
	v_fma_f32 v156, v54, v54, -1.0
	v_mul_f32_e32 v53, v53, v70
	s_waitcnt lgkmcnt(0)
	v_lshlrev_b32_e32 v70, 16, v129
	v_add_f32_e32 v71, v190, v72
	v_mul_f32_e32 v55, v55, v70
	v_mul_f32_e32 v71, 0xbfb8aa3b, v71
	v_exp_f32_e32 v71, v71
	v_add_f32_e32 v56, 1.0, v56
	v_cmp_lt_f32_e32 vcc, s76, v154
	v_rcp_f32_e32 v56, v56
	s_waitcnt lgkmcnt(0)
	v_lshlrev_b32_e32 v72, 16, v130
	v_add_f32_e32 v70, 1.0, v71
	v_add_f32_e32 v57, v189, v57
	v_cndmask_b32_e32 v154, v156, v155, vcc
	v_rcp_f32_e32 v71, v70
	v_mul_f32_e32 v57, 0xbfb8aa3b, v57
	v_sqrt_f32_e64 v154, -v154
	v_exp_f32_e32 v57, v57
	v_mul_f32_e32 v56, v193, v56
	v_exp_f32_e32 v70, v56
	v_mul_f32_e32 v56, 0x3fb17218, v56
	v_mul_f32_e32 v71, v71, v72
	v_add_f32_e32 v72, v190, v73
	v_mul_f32_e32 v55, v154, v55
	v_fmamk_f32 v154, v56, 0x3c088888, v186
	v_mul_f32_e32 v72, 0xbfb8aa3b, v72
	v_add_f32_e32 v57, 1.0, v57
	v_fmaak_f32 v154, v56, v154, 0x3e2aaaab
	v_exp_f32_e32 v72, v72
	v_rcp_f32_e32 v57, v57
	v_fma_f32 v154, v56, v154, 0.5
	v_fma_f32 v154, v56, v154, 1.0
	v_mul_f32_e32 v154, v56, v154
	v_fma_f32 v155, v70, v70, -1.0
	v_cmp_lt_f32_e32 vcc, s76, v56
	v_add_f32_e32 v72, 1.0, v72
	v_mul_f32_e32 v57, v193, v57
	v_cndmask_b32_e32 v56, v155, v154, vcc
	v_rcp_f32_e32 v154, v72
	v_exp_f32_e32 v72, v57
	v_mul_f32_e32 v57, 0x3fb17218, v57
	v_fmamk_f32 v155, v57, 0x3c088888, v186
	v_fmaak_f32 v155, v57, v155, 0x3e2aaaab
	v_fma_f32 v155, v57, v155, 0.5
	v_fma_f32 v155, v57, v155, 1.0
	v_sqrt_f32_e64 v56, -v56
	v_mul_f32_e32 v155, v57, v155
	v_fma_f32 v156, v72, v72, -1.0
	v_cmp_lt_f32_e32 vcc, s76, v57
	v_mul_f32_e32 v71, v56, v71
	s_waitcnt lgkmcnt(0)
	v_lshlrev_b32_e32 v56, 16, v131
	v_cndmask_b32_e32 v57, v156, v155, vcc
	v_sqrt_f32_e64 v57, -v57
	v_mul_f32_e32 v56, v154, v56
	v_add_f32_e32 v60, v189, v60
	v_mul_f32_e32 v60, 0xbfb8aa3b, v60
	v_mul_f32_e32 v73, v57, v56
	v_add_f32_e32 v57, v189, v58
	v_add_f32_e32 v58, v190, v74
	v_mul_f32_e32 v58, 0xbfb8aa3b, v58
	v_exp_f32_e32 v58, v58
	v_mul_f32_e32 v57, 0xbfb8aa3b, v57
	v_exp_f32_e32 v57, v57
	s_waitcnt lgkmcnt(0)
	v_lshlrev_b32_e32 v74, 16, v132
	v_add_f32_e32 v56, 1.0, v58
	v_rcp_f32_e32 v58, v56
	v_add_f32_e32 v57, 1.0, v57
	v_rcp_f32_e32 v57, v57
	v_exp_f32_e32 v60, v60
	v_mul_f32_e32 v74, v58, v74
	v_add_f32_e32 v58, v189, v59
	v_mul_f32_e32 v58, 0xbfb8aa3b, v58
	v_exp_f32_e32 v58, v58
	v_mul_f32_e32 v57, v193, v57
	v_exp_f32_e32 v56, v57
	v_mul_f32_e32 v57, 0x3fb17218, v57
	v_fmamk_f32 v154, v57, 0x3c088888, v186
	v_fmaak_f32 v154, v57, v154, 0x3e2aaaab
	v_add_f32_e32 v58, 1.0, v58
	v_fma_f32 v154, v57, v154, 0.5
	v_add_f32_e32 v59, v190, v75
	v_rcp_f32_e32 v58, v58
	v_fma_f32 v154, v57, v154, 1.0
	v_mul_f32_e32 v59, 0xbfb8aa3b, v59
	v_mul_f32_e32 v154, v57, v154
	v_fma_f32 v155, v56, v56, -1.0
	v_exp_f32_e32 v59, v59
	v_cmp_lt_f32_e32 vcc, s76, v57
	v_add_f32_e32 v59, 1.0, v59
	v_cndmask_b32_e32 v57, v155, v154, vcc
	v_mul_f32_e32 v154, v193, v58
	v_exp_f32_e32 v58, v154
	v_mul_f32_e32 v154, 0x3fb17218, v154
	v_sqrt_f32_e64 v57, -v57
	v_fmamk_f32 v155, v154, 0x3c088888, v186
	v_rcp_f32_e32 v59, v59
	v_fmaak_f32 v155, v154, v155, 0x3e2aaaab
	v_fma_f32 v155, v154, v155, 0.5
	v_fma_f32 v155, v154, v155, 1.0
	v_mul_f32_e32 v155, v154, v155
	v_fma_f32 v156, v58, v58, -1.0
	v_mul_f32_e32 v57, v57, v74
	s_waitcnt lgkmcnt(0)
	v_lshlrev_b32_e32 v74, 16, v133
	v_add_f32_e32 v75, v190, v76
	v_mul_f32_e32 v59, v59, v74
	v_mul_f32_e32 v75, 0xbfb8aa3b, v75
	v_exp_f32_e32 v75, v75
	v_add_f32_e32 v60, 1.0, v60
	v_cmp_lt_f32_e32 vcc, s76, v154
	v_rcp_f32_e32 v60, v60
	s_waitcnt lgkmcnt(0)
	v_lshlrev_b32_e32 v76, 16, v134
	v_add_f32_e32 v74, 1.0, v75
	v_add_f32_e32 v61, v189, v61
	v_cndmask_b32_e32 v154, v156, v155, vcc
	v_rcp_f32_e32 v75, v74
	v_mul_f32_e32 v61, 0xbfb8aa3b, v61
	v_sqrt_f32_e64 v154, -v154
	v_exp_f32_e32 v61, v61
	v_mul_f32_e32 v60, v193, v60
	v_exp_f32_e32 v74, v60
	v_mul_f32_e32 v60, 0x3fb17218, v60
	v_mul_f32_e32 v75, v75, v76
	v_add_f32_e32 v76, v190, v77
	v_mul_f32_e32 v59, v154, v59
	v_fmamk_f32 v154, v60, 0x3c088888, v186
	v_mul_f32_e32 v76, 0xbfb8aa3b, v76
	v_add_f32_e32 v61, 1.0, v61
	v_fmaak_f32 v154, v60, v154, 0x3e2aaaab
	v_exp_f32_e32 v76, v76
	v_rcp_f32_e32 v61, v61
	v_fma_f32 v154, v60, v154, 0.5
	v_fma_f32 v154, v60, v154, 1.0
	v_mul_f32_e32 v154, v60, v154
	v_fma_f32 v155, v74, v74, -1.0
	v_cmp_lt_f32_e32 vcc, s76, v60
	v_add_f32_e32 v76, 1.0, v76
	v_mul_f32_e32 v61, v193, v61
	v_cndmask_b32_e32 v60, v155, v154, vcc
	v_rcp_f32_e32 v154, v76
	v_exp_f32_e32 v76, v61
	v_mul_f32_e32 v61, 0x3fb17218, v61
	v_fmamk_f32 v155, v61, 0x3c088888, v186
	v_fmaak_f32 v155, v61, v155, 0x3e2aaaab
	v_fma_f32 v155, v61, v155, 0.5
	v_fma_f32 v155, v61, v155, 1.0
	v_sqrt_f32_e64 v60, -v60
	v_mul_f32_e32 v155, v61, v155
	v_fma_f32 v156, v76, v76, -1.0
	v_cmp_lt_f32_e32 vcc, s76, v61
	v_mul_f32_e32 v75, v60, v75
	s_waitcnt lgkmcnt(0)
; __device__ __forceinline__ float bf2f(bf16_t b) { return __uint_as_float(((unsigned)b) << 16); }
; __device__ __forceinline__ void scan_loadw(PP p, int dir, int n, int ct, int l31, int hl, ScanW& w) {
;     unsigned chv = (unsigned)(32 * ct + l31); asm volatile("" : "+v"(chv));
;     const unsigned ch = (unsigned)(dir * 512 + 64 * n) + chv;
;     w.ba = p->lru_b_a[ch]; w.bi = p->lru_b_i[ch];
;     w.sp8l2 = ((const float*)(p->ws + WS_SP8))[ch] * 1.4426950408889634f;
;     const bf16_t* wa_b = (const bf16_t*)(p->ws + WS_LRU) + (size_t)((dir * 2 + 0) * 8 + n) * 4096;
;     const bf16_t* wi_b = (const bf16_t*)(p->ws + WS_LRU) + (size_t)((dir * 2 + 1) * 8 + n) * 4096;
;     const unsigned lo = chv * 64u + 8u * (unsigned)hl;
; #pragma unroll
;     for (int st = 0; st < 4; ++st) { w.wfa[st] = *(const bf16x8*)(wa_b + lo + 16 * st); w.wfi[st] = *(const bf16x8*)(wi_b + lo + 16 * st); }
; template <int DIR>
; __device__ __forceinline__ void scan_dir(PP p, const bf16_t* xs, const ScanW& w, ScanW& wn, int ndir, int nct, bool do_next, int n, int ct, int l31, int hl, int id, int rowbase, bool latent, float (&hf)[2][16]) {
;     ...
;         for (int i = 0; i < 16; ++i) {
;             const int token = 32 * rt + 8 * (i >> 2) + 4 * hl + (i & 3);
;             const float xv = bf2f(xs[token * XS + ch]);
;             const float rr = fast_sigmoid(ga[i] + ba), ii = fast_sigmoid(gi[i] + bi);
;             const float la2 = rr * sp8l2;
;             const float av = __builtin_amdgcn_exp2f(la2);
;             const float t2 = la2 * 1.3862943611f;
;             float em1p = t2 * (1.0f + t2 * (0.5f + t2 * (0.16666667f + t2 * (0.041666668f + t2 * 0.0083333333f)))), em1e = __builtin_fmaf(av, av, -1.0f);
;             asm volatile("" : "+v"(em1p), "+v"(em1e));
;             const float em1 = (t2 > -0.1f) ? em1p : em1e;
;             a[rt][i] = av; u[rt][i] = __builtin_amdgcn_sqrtf(-em1) * (ii * xv);
;         }
;     }
;     float Ao[8], Ho[8], Ap[8], Hp[8];
; #pragma unroll
;     for (int k = 0; k < 8; ++k) {
;         const int rt = k >> 2, g = k & 3;
;         float H = 0.f, A = 1.f;
; #pragma unroll
;         for (int jj = 0; jj < 4; ++jj) { const int j = DIR ? 3 - jj : jj; const float av = a[rt][4 * g + j]; H = av * H + u[rt][4 * g + j]; A *= av; }
;         Ao[k] = A; Ho[k] = H; Ap[k] = __shfl_xor(A, 32); Hp[k] = __shfl_xor(H, 32);
;     }
	v_lshlrev_b32_e32 v60, 16, v135
	v_cndmask_b32_e32 v61, v156, v155, vcc
	v_sqrt_f32_e64 v61, -v61
	v_mul_f32_e32 v60, v154, v60
	v_add_f32_e32 v64, v189, v64
	v_mul_f32_e32 v64, 0xbfb8aa3b, v64
	v_mul_f32_e32 v77, v61, v60
	v_add_f32_e32 v61, v189, v62
	v_add_f32_e32 v62, v190, v78
	v_mul_f32_e32 v62, 0xbfb8aa3b, v62
	v_mul_f32_e32 v61, 0xbfb8aa3b, v61
	v_exp_f32_e32 v62, v62
	v_exp_f32_e32 v61, v61
	s_waitcnt lgkmcnt(0)
	v_lshlrev_b32_e32 v78, 16, v136
	v_exp_f32_e32 v64, v64
	v_add_f32_e32 v60, 1.0, v62
	v_add_f32_e32 v61, 1.0, v61
	v_rcp_f32_e32 v62, v60
	v_rcp_f32_e32 v61, v61
	v_add_f32_e32 v65, v189, v65
	v_mul_f32_e32 v65, 0xbfb8aa3b, v65
	v_mul_f32_e32 v78, v62, v78
	v_add_f32_e32 v62, v189, v63
	v_mul_f32_e32 v61, v193, v61
	v_mul_f32_e32 v62, 0xbfb8aa3b, v62
	v_exp_f32_e32 v60, v61
	v_mul_f32_e32 v61, 0x3fb17218, v61
	v_exp_f32_e32 v62, v62
	v_fmamk_f32 v154, v61, 0x3c088888, v186
	v_fmaak_f32 v154, v61, v154, 0x3e2aaaab
	v_fma_f32 v154, v61, v154, 0.5
	v_fma_f32 v154, v61, v154, 1.0
	v_add_f32_e32 v62, 1.0, v62
	v_mul_f32_e32 v154, v61, v154
	v_fma_f32 v155, v60, v60, -1.0
	v_cmp_lt_f32_e32 vcc, s76, v61
	v_add_f32_e32 v63, v190, v79
	v_rcp_f32_e32 v62, v62
	v_mul_f32_e32 v63, 0xbfb8aa3b, v63
	v_cndmask_b32_e32 v61, v155, v154, vcc
	v_sqrt_f32_e64 v61, -v61
	v_exp_f32_e32 v63, v63
	v_mul_f32_e32 v154, v193, v62
	v_exp_f32_e32 v62, v154
	v_mul_f32_e32 v154, 0x3fb17218, v154
	v_add_f32_e32 v63, 1.0, v63
	v_fmamk_f32 v155, v154, 0x3c088888, v186
	v_mul_f32_e32 v61, v61, v78
	s_waitcnt lgkmcnt(0)
	v_lshlrev_b32_e32 v78, 16, v137
	v_add_f32_e32 v79, v190, v80
	v_rcp_f32_e32 v63, v63
	v_fmaak_f32 v155, v154, v155, 0x3e2aaaab
	v_mul_f32_e32 v79, 0xbfb8aa3b, v79
	v_fma_f32 v155, v154, v155, 0.5
	v_exp_f32_e32 v79, v79
	v_exp_f32_e32 v65, v65
	v_fma_f32 v155, v154, v155, 1.0
	v_mul_f32_e32 v155, v154, v155
	v_fma_f32 v156, v62, v62, -1.0
	v_add_f32_e32 v64, 1.0, v64
	v_cmp_lt_f32_e32 vcc, s76, v154
	v_mul_f32_e32 v63, v63, v78
	v_rcp_f32_e32 v64, v64
	v_cndmask_b32_e32 v154, v156, v155, vcc
	v_add_f32_e32 v79, 1.0, v79
	v_add_f32_e32 v65, 1.0, v65
	v_sqrt_f32_e64 v154, -v154
	v_rcp_f32_e32 v79, v79
	v_rcp_f32_e32 v65, v65
	v_mul_f32_e32 v80, v193, v64
	s_waitcnt lgkmcnt(0)
	v_lshlrev_b32_e32 v78, 16, v138
	v_exp_f32_e32 v64, v80
	v_mul_f32_e32 v80, 0x3fb17218, v80
	v_fma_f32 v156, 0, v205, v211
	v_mul_f32_e32 v63, v154, v63
	v_fmamk_f32 v154, v80, 0x3c088888, v186
	v_mul_f32_e32 v78, v79, v78
	v_add_f32_e32 v79, v190, v81
	v_mul_f32_e32 v65, v193, v65
	v_fma_f32 v156, v204, v156, v208
	v_fmaak_f32 v154, v80, v154, 0x3e2aaaab
	v_mul_f32_e32 v79, 0xbfb8aa3b, v79
	v_exp_f32_e32 v213, v65
	v_mul_f32_e32 v65, 0x3fb17218, v65
	v_fma_f32 v156, v42, v156, v43
	v_fma_f32 v154, v80, v154, 0.5
	v_exp_f32_e32 v79, v79
	v_fmamk_f32 v81, v65, 0x3c088888, v186
	v_fma_f32 v216, v40, v156, v41
	v_fma_f32 v156, 0, v207, v210
	v_fma_f32 v154, v80, v154, 1.0
	v_fmaak_f32 v81, v65, v81, 0x3e2aaaab
	v_fma_f32 v156, v206, v156, v209
	v_mul_f32_e32 v154, v80, v154
	v_fma_f32 v155, v64, v64, -1.0
	v_fma_f32 v81, v65, v81, 0.5
	v_fma_f32 v156, v45, v156, v48
	v_cmp_lt_f32_e32 vcc, s76, v80
	ds_read_u16 v0, v0 offset:61360
	v_fma_f32 v81, v65, v81, 1.0
	v_fma_f32 v221, v44, v156, v47
	v_fma_f32 v156, 0, v68, v69
	v_cndmask_b32_e32 v80, v155, v154, vcc
	v_add_f32_e32 v79, 1.0, v79
	v_mul_f32_e32 v81, v65, v81
	v_fma_f32 v154, v213, v213, -1.0
	v_cmp_lt_f32_e32 vcc, s76, v65
	v_fma_f32 v156, v66, v156, v67
	v_rcp_f32_e32 v79, v79
	v_fma_f32 v156, v50, v156, v51
	v_cndmask_b32_e32 v65, v154, v81, vcc
	v_sqrt_f32_e64 v65, -v65
	v_mul_f32_e32 v158, v45, v158
	v_fma_f32 v225, v46, v156, v49
	v_fma_f32 v156, 0, v72, v73
	v_mul_f32_e32 v222, v44, v158
	v_mul_f32_e32 v158, v68, v66
	v_fma_f32 v156, v70, v156, v71
	v_sqrt_f32_e64 v80, -v80
	s_waitcnt lgkmcnt(0)
	v_lshlrev_b32_e32 v0, 16, v0
	v_mul_f32_e32 v158, v50, v158
	v_fma_f32 v156, v54, v156, v55
	v_mul_f32_e32 v0, v79, v0
	v_mul_f32_e32 v226, v46, v158
	v_mul_f32_e32 v158, v72, v70
	v_fma_f32 v229, v52, v156, v53
	v_fma_f32 v156, 0, v76, v77
	v_mul_f32_e32 v214, v65, v0
	v_and_b32_e32 v65, 64, v188
	v_mul_f32_e32 v158, v54, v158
	v_fma_f32 v156, v74, v156, v75
	v_xor_b32_e32 v0, 32, v188
	v_add_u32_e32 v65, 64, v65
	v_mul_f32_e32 v230, v52, v158
	v_mul_f32_e32 v158, v76, v74
	v_fma_f32 v156, v58, v156, v59
	v_mul_f32_e32 v81, v80, v78
	v_cmp_lt_i32_e32 vcc, v0, v65
	v_fma_f32 v65, 0, v198, v199
	v_fma_f32 v154, 0, v202, v203
	v_mul_f32_e32 v158, v58, v158
	v_fma_f32 v233, v56, v156, v57
	v_fma_f32 v156, 0, v213, v214
	v_fma_f32 v65, v196, v65, v197
	v_mul_f32_e32 v78, v198, v196
	v_fma_f32 v154, v200, v154, v201
	v_mul_f32_e32 v155, v202, v200
	v_mul_f32_e32 v234, v56, v158
	v_fma_f32 v156, v64, v156, v81
	v_mul_f32_e32 v158, v213, v64
	v_cndmask_b32_e32 v0, v188, v0, vcc
	v_fma_f32 v65, v147, v65, v195
	v_mul_f32_e32 v78, v147, v78
	v_fma_f32 v154, v38, v154, v39
	v_mul_f32_e32 v155, v38, v155
	v_fma_f32 v156, v62, v156, v63
	v_mul_f32_e32 v159, v62, v158
	v_lshlrev_b32_e32 v0, 2, v0
	v_fma_f32 v65, v34, v65, v35
	v_mul_f32_e32 v78, v34, v78
	v_fma_f32 v154, v36, v154, v37
	v_mul_f32_e32 v155, v36, v155
	v_fma_f32 v158, v60, v156, v61
	v_mul_f32_e32 v156, v60, v159
	ds_bpermute_b32 v79, v0, v78
	ds_bpermute_b32 v80, v0, v65
	ds_bpermute_b32 v212, v0, v155
	ds_bpermute_b32 v215, v0, v154
	ds_bpermute_b32 v218, v0, v217
	ds_bpermute_b32 v219, v0, v216
	ds_bpermute_b32 v223, v0, v222
	ds_bpermute_b32 v224, v0, v221
	ds_bpermute_b32 v227, v0, v226
	ds_bpermute_b32 v228, v0, v225
	ds_bpermute_b32 v231, v0, v230
	ds_bpermute_b32 v232, v0, v229
	ds_bpermute_b32 v235, v0, v234
	ds_bpermute_b32 v236, v0, v233
	ds_bpermute_b32 v220, v0, v156
	ds_bpermute_b32 v237, v0, v158
	s_andn2_b64 vcc, exec, s[4:5]
	s_cbranch_vccnz .LBB0_447
	v_or_b32_e32 v118, 32, v148
	s_load_dwordx2 s[4:5], s[8:9], 0x58
	s_load_dwordx2 s[44:45], s[8:9], 0x68
	v_add_u32_e32 v0, s33, v118
	v_lshlrev_b64 v[114:115], 2, v[0:1]
	v_lshl_or_b32 v0, v118, 6, v149
	s_waitcnt lgkmcnt(0)
	v_lshl_add_u64 v[116:117], s[4:5], 0, v[114:115]
	global_load_dword v192, v[116:117], off
	v_lshl_add_u64 v[116:117], s[44:45], 0, v[114:115]
	global_load_dword v191, v[116:117], off
	v_lshlrev_b64 v[116:117], 1, v[0:1]
	v_lshl_add_u64 v[114:115], s[12:13], 0, v[114:115]
	v_lshl_add_u64 v[138:139], s[14:15], 0, v[116:117]
	v_lshl_add_u64 v[142:143], s[18:19], 0, v[116:117]
	global_load_dword v255, v[114:115], off
	s_nop 0
	global_load_dwordx4 v[114:117], v[138:139], off
	global_load_dwordx4 v[118:121], v[138:139], off offset:32
	global_load_dwordx4 v[122:125], v[138:139], off offset:64
	global_load_dwordx4 v[126:129], v[142:143], off offset:32
	global_load_dwordx4 v[130:133], v[142:143], off offset:64
	global_load_dwordx4 v[134:137], v[142:143], off
	s_nop 0
	global_load_dwordx4 v[138:141], v[138:139], off offset:96
	s_nop 0
	global_load_dwordx4 v[142:145], v[142:143], off offset:96
